# removed the back-to-back s_setprio 0 / s_setprio 1 pairs inside the 32-MFMA blocks of the GEMM K-loops
# speedup vs baseline: 1.0291x; 1.0005x over previous
.LBB0_81:
	s_add_u32 s6, s10, 0x100
	s_addc_u32 s7, s11, 0
	s_add_i32 s80, 0, 0x10000
	s_cmp_eq_u32 s86, 12
	s_cselect_b32 s51, s67, s7
	s_cselect_b32 s50, s66, s6
	s_cselect_b32 s49, s9, vcc_hi
	s_cselect_b32 s48, s65, vcc_lo
	s_add_i32 s58, 0, 0x14000
	s_waitcnt vmcnt(0)
	v_add_u32_e32 v58, s80, v241
	v_add_u32_e32 v82, s58, v241
	ds_read_b128 v[42:45], v58
	ds_read_b128 v[46:49], v58 offset:1024
	ds_read_b128 v[50:53], v58 offset:2048
	ds_read_b128 v[58:61], v58 offset:3072
	ds_read_b128 v[70:73], v82
	ds_read_b128 v[74:77], v82 offset:1024
	ds_read_b128 v[78:81], v82 offset:2048
	ds_read_b128 v[82:85], v82 offset:3072
	v_lshl_add_u64 v[204:205], s[10:11], 0, v[202:203]
	s_add_i32 m0, s40, 0xc000
	ds_read_b128 v[98:101], v242
	ds_read_b128 v[122:125], v242 offset:1024
	ds_read_b128 v[134:137], v242 offset:2048
	ds_read_b128 v[174:177], v242 offset:3072
	ds_read_b128 v[178:181], v242 offset:4096
	ds_read_b128 v[182:185], v242 offset:5120
	ds_read_b128 v[186:189], v242 offset:6144
	ds_read_b128 v[190:193], v242 offset:7168
	global_load_lds_dwordx4 v[204:205], off
	v_lshl_add_u64 v[204:205], s[10:11], 0, v[222:223]
	s_add_i32 m0, s40, 0xe000
	s_nop 0
	global_load_lds_dwordx4 v[204:205], off
	s_waitcnt vmcnt(8)
	s_waitcnt lgkmcnt(0)
	s_barrier
	s_setprio 1
	s_waitcnt lgkmcnt(0)
	v_mfma_f32_16x16x32_bf16 v[170:173], v[42:45], v[98:101], v[170:173]
	v_mfma_f32_16x16x32_bf16 v[166:169], v[50:53], v[98:101], v[166:169]
	v_mfma_f32_16x16x32_bf16 v[154:157], v[42:45], v[134:137], v[154:157]
	v_mfma_f32_16x16x32_bf16 v[150:153], v[50:53], v[134:137], v[150:153]
	v_mfma_f32_16x16x32_bf16 v[138:141], v[42:45], v[178:181], v[138:141]
	v_mfma_f32_16x16x32_bf16 v[130:133], v[50:53], v[178:181], v[130:133]
	v_mfma_f32_16x16x32_bf16 v[118:121], v[42:45], v[186:189], v[118:121]
	v_mfma_f32_16x16x32_bf16 v[110:113], v[50:53], v[186:189], v[110:113]
	v_mfma_f32_16x16x32_bf16 v[170:173], v[46:49], v[122:125], v[170:173]
	v_mfma_f32_16x16x32_bf16 v[166:169], v[58:61], v[122:125], v[166:169]
	v_mfma_f32_16x16x32_bf16 v[154:157], v[46:49], v[174:177], v[154:157]
	v_mfma_f32_16x16x32_bf16 v[150:153], v[58:61], v[174:177], v[150:153]
	v_mfma_f32_16x16x32_bf16 v[138:141], v[46:49], v[182:185], v[138:141]
	v_mfma_f32_16x16x32_bf16 v[130:133], v[58:61], v[182:185], v[130:133]
	v_mfma_f32_16x16x32_bf16 v[118:121], v[46:49], v[190:193], v[118:121]
	v_mfma_f32_16x16x32_bf16 v[110:113], v[58:61], v[190:193], v[110:113]
	v_mfma_f32_16x16x32_bf16 v[158:161], v[70:73], v[98:101], v[158:161]
	v_mfma_f32_16x16x32_bf16 v[98:101], v[78:81], v[98:101], v[162:165]
	v_mfma_f32_16x16x32_bf16 v[114:117], v[70:73], v[178:181], v[114:117]
	v_mfma_f32_16x16x32_bf16 v[126:129], v[78:81], v[178:181], v[126:129]
	v_mfma_f32_16x16x32_bf16 v[102:105], v[70:73], v[186:189], v[102:105]
	v_mfma_f32_16x16x32_bf16 v[106:109], v[78:81], v[186:189], v[106:109]
	v_mfma_f32_16x16x32_bf16 v[158:161], v[74:77], v[122:125], v[158:161]
	v_mfma_f32_16x16x32_bf16 v[98:101], v[82:85], v[122:125], v[98:101]
	v_mfma_f32_16x16x32_bf16 v[122:125], v[70:73], v[134:137], v[142:145]
	v_mfma_f32_16x16x32_bf16 v[134:137], v[78:81], v[134:137], v[146:149]
	v_mfma_f32_16x16x32_bf16 v[114:117], v[74:77], v[182:185], v[114:117]
	v_mfma_f32_16x16x32_bf16 v[126:129], v[82:85], v[182:185], v[126:129]
	v_mfma_f32_16x16x32_bf16 v[102:105], v[74:77], v[190:193], v[102:105]
	v_mfma_f32_16x16x32_bf16 v[106:109], v[82:85], v[190:193], v[106:109]
	v_mfma_f32_16x16x32_bf16 v[122:125], v[74:77], v[174:177], v[122:125]
	v_mfma_f32_16x16x32_bf16 v[134:137], v[82:85], v[174:177], v[134:137]
	s_setprio 0
	s_barrier
	s_add_i32 s10, s80, s37
	v_lshl_add_u64 v[208:209], s[48:49], 0, v[196:197]
	s_mov_b32 m0, s10
	ds_read_b128 v[142:145], v242 offset:16384
	ds_read_b128 v[146:149], v242 offset:17408
	ds_read_b128 v[162:165], v242 offset:18432
	ds_read_b128 v[174:177], v242 offset:19456
	ds_read_b128 v[178:181], v242 offset:20480
	ds_read_b128 v[182:185], v242 offset:21504
	ds_read_b128 v[186:189], v242 offset:22528
	ds_read_b128 v[190:193], v242 offset:23552
	global_load_lds_dwordx4 v[208:209], off
	s_add_i32 m0, s10, 0x2000
	s_add_u32 s10, s48, 0x40000
	v_lshl_add_u64 v[210:211], s[48:49], 0, v[200:201]
	s_addc_u32 s11, s49, 0
	s_add_i32 s58, s58, s37
	global_load_lds_dwordx4 v[210:211], off
	v_lshl_add_u64 v[204:205], s[10:11], 0, v[196:197]
	s_mov_b32 m0, s58
	v_lshl_add_u64 v[212:213], s[50:51], 0, v[194:195]
	global_load_lds_dwordx4 v[204:205], off
	v_lshl_add_u64 v[204:205], s[10:11], 0, v[200:201]
	s_add_i32 m0, s58, 0x2000
	v_lshl_add_u64 v[214:215], s[50:51], 0, v[198:199]
	global_load_lds_dwordx4 v[204:205], off
	s_mov_b32 m0, s40
	s_nop 0
	global_load_lds_dwordx4 v[212:213], off
	s_mov_b32 m0, s57
	s_nop 0
	global_load_lds_dwordx4 v[214:215], off
	s_waitcnt vmcnt(8)
	s_waitcnt lgkmcnt(0)
	s_barrier
	s_setprio 1
	s_waitcnt lgkmcnt(0)
	v_mfma_f32_16x16x32_bf16 v[94:97], v[42:45], v[142:145], v[94:97]
	v_mfma_f32_16x16x32_bf16 v[90:93], v[50:53], v[142:145], v[90:93]
	v_mfma_f32_16x16x32_bf16 v[62:65], v[42:45], v[162:165], v[62:65]
	v_mfma_f32_16x16x32_bf16 v[54:57], v[50:53], v[162:165], v[54:57]
	v_mfma_f32_16x16x32_bf16 v[30:33], v[42:45], v[178:181], v[30:33]
	v_mfma_f32_16x16x32_bf16 v[26:29], v[50:53], v[178:181], v[26:29]
	v_mfma_f32_16x16x32_bf16 v[18:21], v[42:45], v[186:189], v[18:21]
	v_mfma_f32_16x16x32_bf16 v[10:13], v[50:53], v[186:189], v[10:13]
	v_mfma_f32_16x16x32_bf16 v[94:97], v[46:49], v[146:149], v[94:97]
	v_mfma_f32_16x16x32_bf16 v[90:93], v[58:61], v[146:149], v[90:93]
	v_mfma_f32_16x16x32_bf16 v[62:65], v[46:49], v[174:177], v[62:65]
	v_mfma_f32_16x16x32_bf16 v[54:57], v[58:61], v[174:177], v[54:57]
	v_mfma_f32_16x16x32_bf16 v[30:33], v[46:49], v[182:185], v[30:33]
	v_mfma_f32_16x16x32_bf16 v[26:29], v[58:61], v[182:185], v[26:29]
	v_mfma_f32_16x16x32_bf16 v[18:21], v[46:49], v[190:193], v[18:21]
	v_mfma_f32_16x16x32_bf16 v[10:13], v[58:61], v[190:193], v[10:13]
	v_mfma_f32_16x16x32_bf16 v[34:37], v[70:73], v[162:165], v[34:37]
	v_mfma_f32_16x16x32_bf16 v[38:41], v[78:81], v[162:165], v[38:41]
	v_mfma_f32_16x16x32_bf16 v[14:17], v[70:73], v[178:181], v[14:17]
	v_mfma_f32_16x16x32_bf16 v[22:25], v[78:81], v[178:181], v[22:25]
	v_mfma_f32_16x16x32_bf16 v[2:5], v[70:73], v[186:189], v[2:5]
	v_mfma_f32_16x16x32_bf16 v[6:9], v[78:81], v[186:189], v[6:9]
	v_mfma_f32_16x16x32_bf16 v[42:45], v[70:73], v[142:145], v[66:69]
	v_mfma_f32_16x16x32_bf16 v[46:49], v[78:81], v[142:145], v[86:89]
	v_mfma_f32_16x16x32_bf16 v[34:37], v[74:77], v[174:177], v[34:37]
	v_mfma_f32_16x16x32_bf16 v[38:41], v[82:85], v[174:177], v[38:41]
	v_mfma_f32_16x16x32_bf16 v[14:17], v[74:77], v[182:185], v[14:17]
	v_mfma_f32_16x16x32_bf16 v[22:25], v[82:85], v[182:185], v[22:25]
	v_mfma_f32_16x16x32_bf16 v[2:5], v[74:77], v[190:193], v[2:5]
	v_mfma_f32_16x16x32_bf16 v[6:9], v[82:85], v[190:193], v[6:9]
	v_mfma_f32_16x16x32_bf16 v[42:45], v[74:77], v[146:149], v[42:45]
	v_mfma_f32_16x16x32_bf16 v[46:49], v[82:85], v[146:149], v[46:49]
	s_setprio 0
	s_barrier
	s_add_i32 s58, 0, 0x18000
	s_add_i32 s80, 0, 0x1c000
	v_add_u32_e32 v70, s58, v241
	v_add_u32_e32 v86, s80, v241
	ds_read_b128 v[50:53], v70
	ds_read_b128 v[58:61], v70 offset:1024
	ds_read_b128 v[66:69], v70 offset:2048
	ds_read_b128 v[70:73], v70 offset:3072
	ds_read_b128 v[74:77], v86
	ds_read_b128 v[78:81], v86 offset:1024
	ds_read_b128 v[82:85], v86 offset:2048
	ds_read_b128 v[174:177], v86 offset:3072
	s_add_u32 s10, s50, 0x40000
	s_addc_u32 s11, s51, 0
	s_mov_b32 m0, s74
	v_lshl_add_u64 v[162:163], s[10:11], 0, v[194:195]
	ds_read_b128 v[86:89], v242 offset:32768
	ds_read_b128 v[142:145], v242 offset:33792
	ds_read_b128 v[146:149], v242 offset:34816
	ds_read_b128 v[178:181], v242 offset:35840
	ds_read_b128 v[182:185], v242 offset:36864
	ds_read_b128 v[186:189], v242 offset:37888
	ds_read_b128 v[190:193], v242 offset:38912
	ds_read_b128 v[204:207], v242 offset:39936
	global_load_lds_dwordx4 v[162:163], off
	v_lshl_add_u64 v[162:163], s[10:11], 0, v[198:199]
	s_mov_b32 m0, s75
	s_nop 0
	global_load_lds_dwordx4 v[162:163], off
	s_waitcnt vmcnt(8)
	s_waitcnt lgkmcnt(0)
	s_barrier
	s_setprio 1
	s_waitcnt lgkmcnt(0)
	v_mfma_f32_16x16x32_bf16 v[162:165], v[50:53], v[86:89], v[170:173]
	v_mfma_f32_16x16x32_bf16 v[170:173], v[58:61], v[142:145], v[162:165]
	v_mfma_f32_16x16x32_bf16 v[162:165], v[66:69], v[86:89], v[166:169]
	v_mfma_f32_16x16x32_bf16 v[154:157], v[50:53], v[146:149], v[154:157]
	v_mfma_f32_16x16x32_bf16 v[150:153], v[66:69], v[146:149], v[150:153]
	v_mfma_f32_16x16x32_bf16 v[138:141], v[50:53], v[182:185], v[138:141]
	v_mfma_f32_16x16x32_bf16 v[130:133], v[66:69], v[182:185], v[130:133]
	v_mfma_f32_16x16x32_bf16 v[118:121], v[50:53], v[190:193], v[118:121]
	v_mfma_f32_16x16x32_bf16 v[110:113], v[66:69], v[190:193], v[110:113]
	v_mfma_f32_16x16x32_bf16 v[166:169], v[70:73], v[142:145], v[162:165]
	v_mfma_f32_16x16x32_bf16 v[154:157], v[58:61], v[178:181], v[154:157]
	v_mfma_f32_16x16x32_bf16 v[150:153], v[70:73], v[178:181], v[150:153]
	v_mfma_f32_16x16x32_bf16 v[138:141], v[58:61], v[186:189], v[138:141]
	v_mfma_f32_16x16x32_bf16 v[130:133], v[70:73], v[186:189], v[130:133]
	v_mfma_f32_16x16x32_bf16 v[118:121], v[58:61], v[204:207], v[118:121]
	v_mfma_f32_16x16x32_bf16 v[110:113], v[70:73], v[204:207], v[110:113]
	v_mfma_f32_16x16x32_bf16 v[158:161], v[74:77], v[86:89], v[158:161]
	v_mfma_f32_16x16x32_bf16 v[86:89], v[82:85], v[86:89], v[98:101]
	v_mfma_f32_16x16x32_bf16 v[162:165], v[174:177], v[142:145], v[86:89]
	v_mfma_f32_16x16x32_bf16 v[86:89], v[74:77], v[146:149], v[122:125]
	v_mfma_f32_16x16x32_bf16 v[158:161], v[78:81], v[142:145], v[158:161]
	v_mfma_f32_16x16x32_bf16 v[142:145], v[78:81], v[178:181], v[86:89]
	v_mfma_f32_16x16x32_bf16 v[86:89], v[82:85], v[146:149], v[134:137]
	v_mfma_f32_16x16x32_bf16 v[146:149], v[174:177], v[178:181], v[86:89]
	v_mfma_f32_16x16x32_bf16 v[86:89], v[74:77], v[182:185], v[114:117]
	v_mfma_f32_16x16x32_bf16 v[114:117], v[78:81], v[186:189], v[86:89]
	v_mfma_f32_16x16x32_bf16 v[86:89], v[82:85], v[182:185], v[126:129]
	v_mfma_f32_16x16x32_bf16 v[126:129], v[174:177], v[186:189], v[86:89]
	v_mfma_f32_16x16x32_bf16 v[86:89], v[74:77], v[190:193], v[102:105]
	v_mfma_f32_16x16x32_bf16 v[102:105], v[78:81], v[204:207], v[86:89]
	v_mfma_f32_16x16x32_bf16 v[86:89], v[82:85], v[190:193], v[106:109]
	v_mfma_f32_16x16x32_bf16 v[106:109], v[174:177], v[204:207], v[86:89]
	s_setprio 0
	s_barrier
	s_add_i32 s10, s58, s37
	v_lshl_add_u64 v[204:205], v[208:209], 0, s[42:43]
	s_mov_b32 m0, s10
	s_nop 1
	ds_read_b128 v[86:89], v242 offset:49152
	ds_read_b128 v[98:101], v242 offset:50176
	ds_read_b128 v[122:125], v242 offset:51200
	ds_read_b128 v[134:137], v242 offset:52224
	ds_read_b128 v[178:181], v242 offset:53248
	ds_read_b128 v[182:185], v242 offset:54272
	ds_read_b128 v[186:189], v242 offset:55296
	ds_read_b128 v[190:193], v242 offset:56320
	global_load_lds_dwordx4 v[204:205], off
	s_add_i32 m0, s10, 0x2000
	s_add_u32 s10, s48, 0x40080
	v_lshl_add_u64 v[204:205], v[210:211], 0, s[42:43]
	s_addc_u32 s11, s49, 0
	s_add_i32 s48, s80, s37
	global_load_lds_dwordx4 v[204:205], off
	v_lshl_add_u64 v[204:205], s[10:11], 0, v[196:197]
	s_mov_b32 m0, s48
	s_nop 0
	global_load_lds_dwordx4 v[204:205], off
	v_lshl_add_u64 v[204:205], s[10:11], 0, v[200:201]
	s_add_i32 m0, s48, 0x2000
	s_nop 0
	global_load_lds_dwordx4 v[204:205], off
	v_lshl_add_u64 v[204:205], v[212:213], 0, s[42:43]
	s_mov_b32 m0, s93
	s_nop 0
	global_load_lds_dwordx4 v[204:205], off
	v_lshl_add_u64 v[204:205], v[214:215], 0, s[42:43]
	s_mov_b32 m0, s94
	s_nop 0
	global_load_lds_dwordx4 v[204:205], off
	s_waitcnt vmcnt(8)
	s_waitcnt lgkmcnt(0)
	s_barrier
	s_setprio 1
	s_waitcnt lgkmcnt(0)
	v_mfma_f32_16x16x32_bf16 v[94:97], v[50:53], v[86:89], v[94:97]
	v_mfma_f32_16x16x32_bf16 v[90:93], v[66:69], v[86:89], v[90:93]
	v_mfma_f32_16x16x32_bf16 v[62:65], v[50:53], v[122:125], v[62:65]
	v_mfma_f32_16x16x32_bf16 v[54:57], v[66:69], v[122:125], v[54:57]
	v_mfma_f32_16x16x32_bf16 v[30:33], v[50:53], v[178:181], v[30:33]
	v_mfma_f32_16x16x32_bf16 v[26:29], v[66:69], v[178:181], v[26:29]
	v_mfma_f32_16x16x32_bf16 v[18:21], v[50:53], v[186:189], v[18:21]
	v_mfma_f32_16x16x32_bf16 v[10:13], v[66:69], v[186:189], v[10:13]
	v_mfma_f32_16x16x32_bf16 v[94:97], v[58:61], v[98:101], v[94:97]
	v_mfma_f32_16x16x32_bf16 v[90:93], v[70:73], v[98:101], v[90:93]
	v_mfma_f32_16x16x32_bf16 v[62:65], v[58:61], v[134:137], v[62:65]
	v_mfma_f32_16x16x32_bf16 v[54:57], v[70:73], v[134:137], v[54:57]
	v_mfma_f32_16x16x32_bf16 v[30:33], v[58:61], v[182:185], v[30:33]
	v_mfma_f32_16x16x32_bf16 v[26:29], v[70:73], v[182:185], v[26:29]
	v_mfma_f32_16x16x32_bf16 v[18:21], v[58:61], v[190:193], v[18:21]
	v_mfma_f32_16x16x32_bf16 v[10:13], v[70:73], v[190:193], v[10:13]
	v_mfma_f32_16x16x32_bf16 v[42:45], v[74:77], v[86:89], v[42:45]
	v_mfma_f32_16x16x32_bf16 v[66:69], v[78:81], v[98:101], v[42:45]
	v_mfma_f32_16x16x32_bf16 v[42:45], v[82:85], v[86:89], v[46:49]
	v_mfma_f32_16x16x32_bf16 v[34:37], v[74:77], v[122:125], v[34:37]
	v_mfma_f32_16x16x32_bf16 v[38:41], v[82:85], v[122:125], v[38:41]
	v_mfma_f32_16x16x32_bf16 v[14:17], v[74:77], v[178:181], v[14:17]
	v_mfma_f32_16x16x32_bf16 v[22:25], v[82:85], v[178:181], v[22:25]
	v_mfma_f32_16x16x32_bf16 v[2:5], v[74:77], v[186:189], v[2:5]
	v_mfma_f32_16x16x32_bf16 v[6:9], v[82:85], v[186:189], v[6:9]
	v_mfma_f32_16x16x32_bf16 v[86:89], v[174:177], v[98:101], v[42:45]
	v_mfma_f32_16x16x32_bf16 v[34:37], v[78:81], v[134:137], v[34:37]
	v_mfma_f32_16x16x32_bf16 v[38:41], v[174:177], v[134:137], v[38:41]
	v_mfma_f32_16x16x32_bf16 v[14:17], v[78:81], v[182:185], v[14:17]
	v_mfma_f32_16x16x32_bf16 v[22:25], v[174:177], v[182:185], v[22:25]
	v_mfma_f32_16x16x32_bf16 v[2:5], v[78:81], v[190:193], v[2:5]
	v_mfma_f32_16x16x32_bf16 v[6:9], v[174:177], v[190:193], v[6:9]
	s_setprio 0
	s_barrier
	s_add_i32 s86, s86, 2
	s_add_u32 vcc_lo, vcc_lo, 0x100
	s_addc_u32 vcc_hi, vcc_hi, 0
	s_cmp_gt_u32 s86, 13
	s_mov_b64 s[10:11], s[6:7]
	s_cbranch_scc0 .LBB0_81
	s_mul_i32 s48, s36, 0xfe
	v_mov_b32_e32 v42, v1
	s_add_i32 s6, s95, s48
	v_mov_b32_e32 v49, 0x3fff
	v_add_u32_e32 v46, s6, v42
	v_add_u32_e32 v43, 16, v46
	v_med3_i32 v42, v46, 0, v49
	v_med3_i32 v43, v43, 0, v49
	v_lshlrev_b32_e32 v42, 4, v42
	v_lshlrev_b32_e32 v43, 4, v43
	global_load_dwordx4 v[182:185], v42, s[18:19]
	global_load_dwordx4 v[178:181], v43, s[18:19]
	v_add_u32_e32 v42, 32, v46
	v_add_u32_e32 v43, 48, v46
	v_add_u32_e32 v47, 0x80, v46
	v_med3_i32 v42, v42, 0, v49
	v_med3_i32 v43, v43, 0, v49
	v_med3_i32 v47, v47, 0, v49
	v_add_u32_e32 v48, 0x90, v46
	v_lshlrev_b32_e32 v42, 4, v42
	v_lshlrev_b32_e32 v43, 4, v43
	v_lshlrev_b32_e32 v47, 4, v47
	v_med3_i32 v48, v48, 0, v49
	global_load_dwordx4 v[174:177], v42, s[18:19]
	s_nop 0
	global_load_dwordx4 v[42:45], v43, s[18:19]
	v_lshlrev_b32_e32 v48, 4, v48
	global_load_dwordx4 v[134:137], v47, s[18:19]
	global_load_dwordx4 v[122:125], v48, s[18:19]
	v_add_u32_e32 v47, 0xa0, v46
	v_add_u32_e32 v46, 0xb0, v46
	v_med3_i32 v47, v47, 0, v49
	v_med3_i32 v46, v46, 0, v49
	v_lshlrev_b32_e32 v47, 4, v47
	v_lshlrev_b32_e32 v46, 4, v46
	global_load_dwordx4 v[98:101], v47, s[18:19]
	s_nop 0
	global_load_dwordx4 v[46:49], v46, s[18:19]
	s_and_b64 vcc, exec, s[26:27]
	s_cbranch_vccz .LBB0_84
	s_barrier

.LBB0_126:
	s_add_u32 s38, s26, 0x100
	s_addc_u32 s39, s27, 0
	s_add_i32 s58, 0, 0x10000
	s_cmp_eq_u32 s77, 40
	s_cselect_b32 s47, s7, s39
	s_cselect_b32 s46, s6, s38
	s_cselect_b32 s45, s23, s75
	s_cselect_b32 s44, s22, s56
	s_add_i32 s80, 0, 0x14000
	v_add_u32_e32 v94, s58, v165
	v_add_u32_e32 v162, s80, v165
	ds_read_b128 v[74:77], v94
	ds_read_b128 v[78:81], v94 offset:1024
	ds_read_b128 v[90:93], v94 offset:2048
	ds_read_b128 v[94:97], v94 offset:3072
	ds_read_b128 v[158:161], v162
	ds_read_b128 v[168:171], v162 offset:1024
	ds_read_b128 v[172:175], v162 offset:2048
	ds_read_b128 v[176:179], v162 offset:3072
	v_lshl_add_u64 v[162:163], s[26:27], 0, v[154:155]
	s_add_i32 m0, s37, 0xc000
	ds_read_b128 v[180:183], v166
	ds_read_b128 v[184:187], v166 offset:1024
	ds_read_b128 v[188:191], v166 offset:2048
	ds_read_b128 v[192:195], v166 offset:3072
	ds_read_b128 v[196:199], v166 offset:4096
	ds_read_b128 v[200:203], v166 offset:5120
	ds_read_b128 v[204:207], v166 offset:6144
	ds_read_b128 v[208:211], v166 offset:7168
	global_load_lds_dwordx4 v[162:163], off
	v_lshl_add_u64 v[162:163], s[26:27], 0, v[156:157]
	s_add_i32 m0, s37, 0xe000
	s_nop 0
	global_load_lds_dwordx4 v[162:163], off
	s_waitcnt vmcnt(8)
	s_waitcnt lgkmcnt(0)
	s_barrier
	s_setprio 1
	s_waitcnt lgkmcnt(0)
	v_mfma_f32_16x16x32_bf16 v[142:145], v[74:77], v[180:183], v[142:145]
	v_mfma_f32_16x16x32_bf16 v[138:141], v[90:93], v[180:183], v[138:141]
	v_mfma_f32_16x16x32_bf16 v[126:129], v[74:77], v[188:191], v[126:129]
	v_mfma_f32_16x16x32_bf16 v[122:125], v[90:93], v[188:191], v[122:125]
	v_mfma_f32_16x16x32_bf16 v[110:113], v[74:77], v[196:199], v[110:113]
	v_mfma_f32_16x16x32_bf16 v[106:109], v[90:93], v[196:199], v[106:109]
	v_mfma_f32_16x16x32_bf16 v[86:89], v[74:77], v[204:207], v[86:89]
	v_mfma_f32_16x16x32_bf16 v[82:85], v[90:93], v[204:207], v[82:85]
	v_mfma_f32_16x16x32_bf16 v[142:145], v[78:81], v[184:187], v[142:145]
	v_mfma_f32_16x16x32_bf16 v[138:141], v[94:97], v[184:187], v[138:141]
	v_mfma_f32_16x16x32_bf16 v[126:129], v[78:81], v[192:195], v[126:129]
	v_mfma_f32_16x16x32_bf16 v[122:125], v[94:97], v[192:195], v[122:125]
	v_mfma_f32_16x16x32_bf16 v[110:113], v[78:81], v[200:203], v[110:113]
	v_mfma_f32_16x16x32_bf16 v[106:109], v[94:97], v[200:203], v[106:109]
	v_mfma_f32_16x16x32_bf16 v[86:89], v[78:81], v[208:211], v[86:89]
	v_mfma_f32_16x16x32_bf16 v[82:85], v[94:97], v[208:211], v[82:85]
	v_mfma_f32_16x16x32_bf16 v[134:137], v[158:161], v[180:183], v[134:137]
	v_mfma_f32_16x16x32_bf16 v[130:133], v[172:175], v[180:183], v[130:133]
	v_mfma_f32_16x16x32_bf16 v[118:121], v[158:161], v[188:191], v[118:121]
	v_mfma_f32_16x16x32_bf16 v[114:117], v[172:175], v[188:191], v[114:117]
	v_mfma_f32_16x16x32_bf16 v[102:105], v[158:161], v[196:199], v[102:105]
	v_mfma_f32_16x16x32_bf16 v[98:101], v[172:175], v[196:199], v[98:101]
	v_mfma_f32_16x16x32_bf16 v[70:73], v[158:161], v[204:207], v[70:73]
	v_mfma_f32_16x16x32_bf16 v[66:69], v[172:175], v[204:207], v[66:69]
	v_mfma_f32_16x16x32_bf16 v[134:137], v[168:171], v[184:187], v[134:137]
	v_mfma_f32_16x16x32_bf16 v[130:133], v[176:179], v[184:187], v[130:133]
	v_mfma_f32_16x16x32_bf16 v[118:121], v[168:171], v[192:195], v[118:121]
	v_mfma_f32_16x16x32_bf16 v[114:117], v[176:179], v[192:195], v[114:117]
	v_mfma_f32_16x16x32_bf16 v[102:105], v[168:171], v[200:203], v[102:105]
	v_mfma_f32_16x16x32_bf16 v[98:101], v[176:179], v[200:203], v[98:101]
	v_mfma_f32_16x16x32_bf16 v[70:73], v[168:171], v[208:211], v[70:73]
	v_mfma_f32_16x16x32_bf16 v[66:69], v[176:179], v[208:211], v[66:69]
	s_setprio 0
	s_barrier
	s_add_i32 s26, s58, s36
	v_lshl_add_u64 v[162:163], s[44:45], 0, v[148:149]
	s_mov_b32 m0, s26
	ds_read_b128 v[180:183], v166 offset:16384
	ds_read_b128 v[184:187], v166 offset:17408
	ds_read_b128 v[188:191], v166 offset:18432
	ds_read_b128 v[192:195], v166 offset:19456
	ds_read_b128 v[196:199], v166 offset:20480
	ds_read_b128 v[200:203], v166 offset:21504
	ds_read_b128 v[204:207], v166 offset:22528
	ds_read_b128 v[208:211], v166 offset:23552
	global_load_lds_dwordx4 v[162:163], off
	s_add_i32 m0, s26, 0x2000
	s_add_u32 s26, s44, 0xb0000
	v_lshl_add_u64 v[212:213], s[44:45], 0, v[152:153]
	s_addc_u32 s27, s45, 0
	s_add_i32 s58, s80, s36
	global_load_lds_dwordx4 v[212:213], off
	v_lshl_add_u64 v[214:215], s[26:27], 0, v[148:149]
	s_mov_b32 m0, s58
	v_lshl_add_u64 v[216:217], s[46:47], 0, v[150:151]
	global_load_lds_dwordx4 v[214:215], off
	v_lshl_add_u64 v[214:215], s[26:27], 0, v[152:153]
	s_add_i32 m0, s58, 0x2000
	s_nop 0
	global_load_lds_dwordx4 v[214:215], off
	v_lshl_add_u64 v[214:215], s[46:47], 0, v[146:147]
	s_mov_b32 m0, s37
	s_nop 0
	global_load_lds_dwordx4 v[214:215], off
	s_mov_b32 m0, s48
	s_nop 0
	global_load_lds_dwordx4 v[216:217], off
	s_waitcnt vmcnt(8)
	s_waitcnt lgkmcnt(0)
	s_barrier
	s_setprio 1
	s_waitcnt lgkmcnt(0)
	v_mfma_f32_16x16x32_bf16 v[62:65], v[74:77], v[180:183], v[62:65]
	v_mfma_f32_16x16x32_bf16 v[58:61], v[90:93], v[180:183], v[58:61]
	v_mfma_f32_16x16x32_bf16 v[46:49], v[74:77], v[188:191], v[46:49]
	v_mfma_f32_16x16x32_bf16 v[42:45], v[90:93], v[188:191], v[42:45]
	v_mfma_f32_16x16x32_bf16 v[30:33], v[74:77], v[196:199], v[30:33]
	v_mfma_f32_16x16x32_bf16 v[26:29], v[90:93], v[196:199], v[26:29]
	v_mfma_f32_16x16x32_bf16 v[14:17], v[74:77], v[204:207], v[14:17]
	v_mfma_f32_16x16x32_bf16 v[10:13], v[90:93], v[204:207], v[10:13]
	v_mfma_f32_16x16x32_bf16 v[62:65], v[78:81], v[184:187], v[62:65]
	v_mfma_f32_16x16x32_bf16 v[58:61], v[94:97], v[184:187], v[58:61]
	v_mfma_f32_16x16x32_bf16 v[46:49], v[78:81], v[192:195], v[46:49]
	v_mfma_f32_16x16x32_bf16 v[42:45], v[94:97], v[192:195], v[42:45]
	v_mfma_f32_16x16x32_bf16 v[30:33], v[78:81], v[200:203], v[30:33]
	v_mfma_f32_16x16x32_bf16 v[26:29], v[94:97], v[200:203], v[26:29]
	v_mfma_f32_16x16x32_bf16 v[14:17], v[78:81], v[208:211], v[14:17]
	v_mfma_f32_16x16x32_bf16 v[10:13], v[94:97], v[208:211], v[10:13]
	v_mfma_f32_16x16x32_bf16 v[54:57], v[158:161], v[180:183], v[54:57]
	v_mfma_f32_16x16x32_bf16 v[50:53], v[172:175], v[180:183], v[50:53]
	v_mfma_f32_16x16x32_bf16 v[38:41], v[158:161], v[188:191], v[38:41]
	v_mfma_f32_16x16x32_bf16 v[34:37], v[172:175], v[188:191], v[34:37]
	v_mfma_f32_16x16x32_bf16 v[22:25], v[158:161], v[196:199], v[22:25]
	v_mfma_f32_16x16x32_bf16 v[18:21], v[172:175], v[196:199], v[18:21]
	v_mfma_f32_16x16x32_bf16 v[6:9], v[158:161], v[204:207], v[6:9]
	v_mfma_f32_16x16x32_bf16 v[2:5], v[172:175], v[204:207], v[2:5]
	v_mfma_f32_16x16x32_bf16 v[54:57], v[168:171], v[184:187], v[54:57]
	v_mfma_f32_16x16x32_bf16 v[50:53], v[176:179], v[184:187], v[50:53]
	v_mfma_f32_16x16x32_bf16 v[38:41], v[168:171], v[192:195], v[38:41]
	v_mfma_f32_16x16x32_bf16 v[34:37], v[176:179], v[192:195], v[34:37]
	v_mfma_f32_16x16x32_bf16 v[22:25], v[168:171], v[200:203], v[22:25]
	v_mfma_f32_16x16x32_bf16 v[18:21], v[176:179], v[200:203], v[18:21]
	v_mfma_f32_16x16x32_bf16 v[6:9], v[168:171], v[208:211], v[6:9]
	v_mfma_f32_16x16x32_bf16 v[2:5], v[176:179], v[208:211], v[2:5]
	s_setprio 0
	s_barrier
	s_add_i32 s58, 0, 0x18000
	s_add_i32 s80, 0, 0x1c000
	v_add_u32_e32 v94, s58, v165
	v_add_u32_e32 v167, s80, v165
	ds_read_b128 v[74:77], v94
	ds_read_b128 v[78:81], v94 offset:1024
	ds_read_b128 v[90:93], v94 offset:2048
	ds_read_b128 v[94:97], v94 offset:3072
	ds_read_b128 v[158:161], v167
	ds_read_b128 v[168:171], v167 offset:1024
	ds_read_b128 v[172:175], v167 offset:2048
	ds_read_b128 v[176:179], v167 offset:3072
	s_add_u32 s26, s46, 0xb0000
	s_addc_u32 s27, s47, 0
	s_mov_b32 m0, s49
	v_lshl_add_u64 v[218:219], s[26:27], 0, v[146:147]
	ds_read_b128 v[180:183], v166 offset:32768
	ds_read_b128 v[184:187], v166 offset:33792
	ds_read_b128 v[188:191], v166 offset:34816
	ds_read_b128 v[192:195], v166 offset:35840
	ds_read_b128 v[196:199], v166 offset:36864
	ds_read_b128 v[200:203], v166 offset:37888
	ds_read_b128 v[204:207], v166 offset:38912
	ds_read_b128 v[208:211], v166 offset:39936
	global_load_lds_dwordx4 v[218:219], off
	v_lshl_add_u64 v[218:219], s[26:27], 0, v[150:151]
	s_mov_b32 m0, s50
	s_nop 0
	global_load_lds_dwordx4 v[218:219], off
	s_waitcnt vmcnt(8)
	s_waitcnt lgkmcnt(0)
	s_barrier
	s_setprio 1
	s_waitcnt lgkmcnt(0)
	v_mfma_f32_16x16x32_bf16 v[142:145], v[74:77], v[180:183], v[142:145]
	v_mfma_f32_16x16x32_bf16 v[138:141], v[90:93], v[180:183], v[138:141]
	v_mfma_f32_16x16x32_bf16 v[126:129], v[74:77], v[188:191], v[126:129]
	v_mfma_f32_16x16x32_bf16 v[122:125], v[90:93], v[188:191], v[122:125]
	v_mfma_f32_16x16x32_bf16 v[110:113], v[74:77], v[196:199], v[110:113]
	v_mfma_f32_16x16x32_bf16 v[106:109], v[90:93], v[196:199], v[106:109]
	v_mfma_f32_16x16x32_bf16 v[86:89], v[74:77], v[204:207], v[86:89]
	v_mfma_f32_16x16x32_bf16 v[82:85], v[90:93], v[204:207], v[82:85]
	v_mfma_f32_16x16x32_bf16 v[142:145], v[78:81], v[184:187], v[142:145]
	v_mfma_f32_16x16x32_bf16 v[138:141], v[94:97], v[184:187], v[138:141]
	v_mfma_f32_16x16x32_bf16 v[126:129], v[78:81], v[192:195], v[126:129]
	v_mfma_f32_16x16x32_bf16 v[122:125], v[94:97], v[192:195], v[122:125]
	v_mfma_f32_16x16x32_bf16 v[110:113], v[78:81], v[200:203], v[110:113]
	v_mfma_f32_16x16x32_bf16 v[106:109], v[94:97], v[200:203], v[106:109]
	v_mfma_f32_16x16x32_bf16 v[86:89], v[78:81], v[208:211], v[86:89]
	v_mfma_f32_16x16x32_bf16 v[82:85], v[94:97], v[208:211], v[82:85]
	v_mfma_f32_16x16x32_bf16 v[134:137], v[158:161], v[180:183], v[134:137]
	v_mfma_f32_16x16x32_bf16 v[130:133], v[172:175], v[180:183], v[130:133]
	v_mfma_f32_16x16x32_bf16 v[118:121], v[158:161], v[188:191], v[118:121]
	v_mfma_f32_16x16x32_bf16 v[114:117], v[172:175], v[188:191], v[114:117]
	v_mfma_f32_16x16x32_bf16 v[102:105], v[158:161], v[196:199], v[102:105]
	v_mfma_f32_16x16x32_bf16 v[98:101], v[172:175], v[196:199], v[98:101]
	v_mfma_f32_16x16x32_bf16 v[70:73], v[158:161], v[204:207], v[70:73]
	v_mfma_f32_16x16x32_bf16 v[66:69], v[172:175], v[204:207], v[66:69]
	v_mfma_f32_16x16x32_bf16 v[134:137], v[168:171], v[184:187], v[134:137]
	v_mfma_f32_16x16x32_bf16 v[130:133], v[176:179], v[184:187], v[130:133]
	v_mfma_f32_16x16x32_bf16 v[118:121], v[168:171], v[192:195], v[118:121]
	v_mfma_f32_16x16x32_bf16 v[114:117], v[176:179], v[192:195], v[114:117]
	v_mfma_f32_16x16x32_bf16 v[102:105], v[168:171], v[200:203], v[102:105]
	v_mfma_f32_16x16x32_bf16 v[98:101], v[176:179], v[200:203], v[98:101]
	v_mfma_f32_16x16x32_bf16 v[70:73], v[168:171], v[208:211], v[70:73]
	v_mfma_f32_16x16x32_bf16 v[66:69], v[176:179], v[208:211], v[66:69]
	s_setprio 0
	s_barrier
	s_add_i32 s26, s58, s36
	v_lshl_add_u64 v[162:163], v[162:163], 0, s[42:43]
	s_mov_b32 m0, s26
	ds_read_b128 v[180:183], v166 offset:49152
	ds_read_b128 v[184:187], v166 offset:50176
	ds_read_b128 v[188:191], v166 offset:51200
	ds_read_b128 v[192:195], v166 offset:52224
	ds_read_b128 v[196:199], v166 offset:53248
	ds_read_b128 v[200:203], v166 offset:54272
	ds_read_b128 v[204:207], v166 offset:55296
	ds_read_b128 v[208:211], v166 offset:56320
	global_load_lds_dwordx4 v[162:163], off
	s_add_i32 m0, s26, 0x2000
	s_add_u32 s26, s44, 0xb0080
	v_lshl_add_u64 v[162:163], v[212:213], 0, s[42:43]
	s_addc_u32 s27, s45, 0
	s_add_i32 s44, s80, s36
	global_load_lds_dwordx4 v[162:163], off
	v_lshl_add_u64 v[162:163], s[26:27], 0, v[148:149]
	s_mov_b32 m0, s44
	s_nop 0
	global_load_lds_dwordx4 v[162:163], off
	v_lshl_add_u64 v[162:163], s[26:27], 0, v[152:153]
	s_add_i32 m0, s44, 0x2000
	s_nop 0
	global_load_lds_dwordx4 v[162:163], off
	v_lshl_add_u64 v[162:163], v[214:215], 0, s[42:43]
	s_mov_b32 m0, s53
	s_nop 0
	global_load_lds_dwordx4 v[162:163], off
	v_lshl_add_u64 v[162:163], v[216:217], 0, s[42:43]
	s_mov_b32 m0, s54
	s_nop 0
	global_load_lds_dwordx4 v[162:163], off
	s_waitcnt vmcnt(8)
	s_waitcnt lgkmcnt(0)
	s_barrier
	s_setprio 1
	s_waitcnt lgkmcnt(0)
	v_mfma_f32_16x16x32_bf16 v[62:65], v[74:77], v[180:183], v[62:65]
	v_mfma_f32_16x16x32_bf16 v[58:61], v[90:93], v[180:183], v[58:61]
	v_mfma_f32_16x16x32_bf16 v[46:49], v[74:77], v[188:191], v[46:49]
	v_mfma_f32_16x16x32_bf16 v[42:45], v[90:93], v[188:191], v[42:45]
	v_mfma_f32_16x16x32_bf16 v[30:33], v[74:77], v[196:199], v[30:33]
	v_mfma_f32_16x16x32_bf16 v[26:29], v[90:93], v[196:199], v[26:29]
	v_mfma_f32_16x16x32_bf16 v[14:17], v[74:77], v[204:207], v[14:17]
	v_mfma_f32_16x16x32_bf16 v[10:13], v[90:93], v[204:207], v[10:13]
	v_mfma_f32_16x16x32_bf16 v[62:65], v[78:81], v[184:187], v[62:65]
	v_mfma_f32_16x16x32_bf16 v[58:61], v[94:97], v[184:187], v[58:61]
	v_mfma_f32_16x16x32_bf16 v[46:49], v[78:81], v[192:195], v[46:49]
	v_mfma_f32_16x16x32_bf16 v[42:45], v[94:97], v[192:195], v[42:45]
	v_mfma_f32_16x16x32_bf16 v[30:33], v[78:81], v[200:203], v[30:33]
	v_mfma_f32_16x16x32_bf16 v[26:29], v[94:97], v[200:203], v[26:29]
	v_mfma_f32_16x16x32_bf16 v[14:17], v[78:81], v[208:211], v[14:17]
	v_mfma_f32_16x16x32_bf16 v[10:13], v[94:97], v[208:211], v[10:13]
	v_mfma_f32_16x16x32_bf16 v[54:57], v[158:161], v[180:183], v[54:57]
	v_mfma_f32_16x16x32_bf16 v[50:53], v[172:175], v[180:183], v[50:53]
	v_mfma_f32_16x16x32_bf16 v[38:41], v[158:161], v[188:191], v[38:41]
	v_mfma_f32_16x16x32_bf16 v[34:37], v[172:175], v[188:191], v[34:37]
	v_mfma_f32_16x16x32_bf16 v[22:25], v[158:161], v[196:199], v[22:25]
	v_mfma_f32_16x16x32_bf16 v[18:21], v[172:175], v[196:199], v[18:21]
	v_mfma_f32_16x16x32_bf16 v[6:9], v[158:161], v[204:207], v[6:9]
	v_mfma_f32_16x16x32_bf16 v[2:5], v[172:175], v[204:207], v[2:5]
	v_mfma_f32_16x16x32_bf16 v[54:57], v[168:171], v[184:187], v[54:57]
	v_mfma_f32_16x16x32_bf16 v[50:53], v[176:179], v[184:187], v[50:53]
	v_mfma_f32_16x16x32_bf16 v[38:41], v[168:171], v[192:195], v[38:41]
	v_mfma_f32_16x16x32_bf16 v[34:37], v[176:179], v[192:195], v[34:37]
	v_mfma_f32_16x16x32_bf16 v[22:25], v[168:171], v[200:203], v[22:25]
	v_mfma_f32_16x16x32_bf16 v[18:21], v[176:179], v[200:203], v[18:21]
	v_mfma_f32_16x16x32_bf16 v[6:9], v[168:171], v[208:211], v[6:9]
	v_mfma_f32_16x16x32_bf16 v[2:5], v[176:179], v[208:211], v[2:5]
	s_setprio 0
	s_barrier
	s_add_i32 s77, s77, 2
	s_add_u32 s56, s56, 0x100
	s_addc_u32 s75, s75, 0
	s_cmp_gt_u32 s77, 41
	s_mov_b64 s[26:27], s[38:39]
	s_cbranch_scc0 .LBB0_126
	s_and_b64 vcc, exec, s[18:19]
	s_cbranch_vccz .LBB0_129
	s_barrier

.LBB0_206:
	s_add_u32 s46, s44, 0x100
	s_addc_u32 s47, s45, 0
	s_add_i32 s86, 0, 0x10000
	s_cmp_eq_u32 s90, 12
	s_cselect_b32 s51, s17, s47
	s_cselect_b32 s50, s21, s46
	s_cselect_b32 s49, s19, s89
	s_cselect_b32 s48, s39, s56
	s_add_i32 s91, 0, 0x14000
	v_add_u32_e32 v94, s86, v165
	v_add_u32_e32 v162, s91, v165
	ds_read_b128 v[74:77], v94
	ds_read_b128 v[78:81], v94 offset:1024
	ds_read_b128 v[90:93], v94 offset:2048
	ds_read_b128 v[94:97], v94 offset:3072
	ds_read_b128 v[158:161], v162
	ds_read_b128 v[168:171], v162 offset:1024
	ds_read_b128 v[172:175], v162 offset:2048
	ds_read_b128 v[176:179], v162 offset:3072
	v_lshl_add_u64 v[162:163], s[44:45], 0, v[154:155]
	s_add_i32 m0, s37, 0xc000
	ds_read_b128 v[180:183], v166
	ds_read_b128 v[184:187], v166 offset:1024
	ds_read_b128 v[188:191], v166 offset:2048
	ds_read_b128 v[192:195], v166 offset:3072
	ds_read_b128 v[196:199], v166 offset:4096
	ds_read_b128 v[200:203], v166 offset:5120
	ds_read_b128 v[204:207], v166 offset:6144
	ds_read_b128 v[208:211], v166 offset:7168
	global_load_lds_dwordx4 v[162:163], off
	v_lshl_add_u64 v[162:163], s[44:45], 0, v[156:157]
	s_add_i32 m0, s37, 0xe000
	s_nop 0
	global_load_lds_dwordx4 v[162:163], off
	s_waitcnt vmcnt(8)
	s_waitcnt lgkmcnt(0)
	s_barrier
	s_setprio 1
	s_waitcnt lgkmcnt(0)
	v_mfma_f32_16x16x32_bf16 v[142:145], v[74:77], v[180:183], v[142:145]
	v_mfma_f32_16x16x32_bf16 v[138:141], v[90:93], v[180:183], v[138:141]
	v_mfma_f32_16x16x32_bf16 v[126:129], v[74:77], v[188:191], v[126:129]
	v_mfma_f32_16x16x32_bf16 v[122:125], v[90:93], v[188:191], v[122:125]
	v_mfma_f32_16x16x32_bf16 v[110:113], v[74:77], v[196:199], v[110:113]
	v_mfma_f32_16x16x32_bf16 v[106:109], v[90:93], v[196:199], v[106:109]
	v_mfma_f32_16x16x32_bf16 v[86:89], v[74:77], v[204:207], v[86:89]
	v_mfma_f32_16x16x32_bf16 v[82:85], v[90:93], v[204:207], v[82:85]
	v_mfma_f32_16x16x32_bf16 v[142:145], v[78:81], v[184:187], v[142:145]
	v_mfma_f32_16x16x32_bf16 v[138:141], v[94:97], v[184:187], v[138:141]
	v_mfma_f32_16x16x32_bf16 v[126:129], v[78:81], v[192:195], v[126:129]
	v_mfma_f32_16x16x32_bf16 v[122:125], v[94:97], v[192:195], v[122:125]
	v_mfma_f32_16x16x32_bf16 v[110:113], v[78:81], v[200:203], v[110:113]
	v_mfma_f32_16x16x32_bf16 v[106:109], v[94:97], v[200:203], v[106:109]
	v_mfma_f32_16x16x32_bf16 v[86:89], v[78:81], v[208:211], v[86:89]
	v_mfma_f32_16x16x32_bf16 v[82:85], v[94:97], v[208:211], v[82:85]
	v_mfma_f32_16x16x32_bf16 v[134:137], v[158:161], v[180:183], v[134:137]
	v_mfma_f32_16x16x32_bf16 v[130:133], v[172:175], v[180:183], v[130:133]
	v_mfma_f32_16x16x32_bf16 v[118:121], v[158:161], v[188:191], v[118:121]
	v_mfma_f32_16x16x32_bf16 v[114:117], v[172:175], v[188:191], v[114:117]
	v_mfma_f32_16x16x32_bf16 v[102:105], v[158:161], v[196:199], v[102:105]
	v_mfma_f32_16x16x32_bf16 v[98:101], v[172:175], v[196:199], v[98:101]
	v_mfma_f32_16x16x32_bf16 v[70:73], v[158:161], v[204:207], v[70:73]
	v_mfma_f32_16x16x32_bf16 v[66:69], v[172:175], v[204:207], v[66:69]
	v_mfma_f32_16x16x32_bf16 v[134:137], v[168:171], v[184:187], v[134:137]
	v_mfma_f32_16x16x32_bf16 v[130:133], v[176:179], v[184:187], v[130:133]
	v_mfma_f32_16x16x32_bf16 v[118:121], v[168:171], v[192:195], v[118:121]
	v_mfma_f32_16x16x32_bf16 v[114:117], v[176:179], v[192:195], v[114:117]
	v_mfma_f32_16x16x32_bf16 v[102:105], v[168:171], v[200:203], v[102:105]
	v_mfma_f32_16x16x32_bf16 v[98:101], v[176:179], v[200:203], v[98:101]
	v_mfma_f32_16x16x32_bf16 v[70:73], v[168:171], v[208:211], v[70:73]
	v_mfma_f32_16x16x32_bf16 v[66:69], v[176:179], v[208:211], v[66:69]
	s_setprio 0
	s_barrier
	s_add_i32 s44, s86, s36
	v_lshl_add_u64 v[162:163], s[48:49], 0, v[148:149]
	s_mov_b32 m0, s44
	ds_read_b128 v[180:183], v166 offset:16384
	ds_read_b128 v[184:187], v166 offset:17408
	ds_read_b128 v[188:191], v166 offset:18432
	ds_read_b128 v[192:195], v166 offset:19456
	ds_read_b128 v[196:199], v166 offset:20480
	ds_read_b128 v[200:203], v166 offset:21504
	ds_read_b128 v[204:207], v166 offset:22528
	ds_read_b128 v[208:211], v166 offset:23552
	global_load_lds_dwordx4 v[162:163], off
	s_add_i32 m0, s44, 0x2000
	s_add_u32 s44, s48, 0x40000
	v_lshl_add_u64 v[212:213], s[48:49], 0, v[152:153]
	s_addc_u32 s45, s49, 0
	s_add_i32 s86, s91, s36
	global_load_lds_dwordx4 v[212:213], off
	v_lshl_add_u64 v[214:215], s[44:45], 0, v[148:149]
	s_mov_b32 m0, s86
	v_lshl_add_u64 v[216:217], s[50:51], 0, v[150:151]
	global_load_lds_dwordx4 v[214:215], off
	v_lshl_add_u64 v[214:215], s[44:45], 0, v[152:153]
	s_add_i32 m0, s86, 0x2000
	s_nop 0
	global_load_lds_dwordx4 v[214:215], off
	v_lshl_add_u64 v[214:215], s[50:51], 0, v[146:147]
	s_mov_b32 m0, s37
	s_nop 0
	global_load_lds_dwordx4 v[214:215], off
	s_mov_b32 m0, s52
	s_nop 0
	global_load_lds_dwordx4 v[216:217], off
	s_waitcnt vmcnt(8)
	s_waitcnt lgkmcnt(0)
	s_barrier
	s_setprio 1
	s_waitcnt lgkmcnt(0)
	v_mfma_f32_16x16x32_bf16 v[62:65], v[74:77], v[180:183], v[62:65]
	v_mfma_f32_16x16x32_bf16 v[58:61], v[90:93], v[180:183], v[58:61]
	v_mfma_f32_16x16x32_bf16 v[46:49], v[74:77], v[188:191], v[46:49]
	v_mfma_f32_16x16x32_bf16 v[42:45], v[90:93], v[188:191], v[42:45]
	v_mfma_f32_16x16x32_bf16 v[30:33], v[74:77], v[196:199], v[30:33]
	v_mfma_f32_16x16x32_bf16 v[26:29], v[90:93], v[196:199], v[26:29]
	v_mfma_f32_16x16x32_bf16 v[14:17], v[74:77], v[204:207], v[14:17]
	v_mfma_f32_16x16x32_bf16 v[10:13], v[90:93], v[204:207], v[10:13]
	v_mfma_f32_16x16x32_bf16 v[62:65], v[78:81], v[184:187], v[62:65]
	v_mfma_f32_16x16x32_bf16 v[58:61], v[94:97], v[184:187], v[58:61]
	v_mfma_f32_16x16x32_bf16 v[46:49], v[78:81], v[192:195], v[46:49]
	v_mfma_f32_16x16x32_bf16 v[42:45], v[94:97], v[192:195], v[42:45]
	v_mfma_f32_16x16x32_bf16 v[30:33], v[78:81], v[200:203], v[30:33]
	v_mfma_f32_16x16x32_bf16 v[26:29], v[94:97], v[200:203], v[26:29]
	v_mfma_f32_16x16x32_bf16 v[14:17], v[78:81], v[208:211], v[14:17]
	v_mfma_f32_16x16x32_bf16 v[10:13], v[94:97], v[208:211], v[10:13]
	v_mfma_f32_16x16x32_bf16 v[54:57], v[158:161], v[180:183], v[54:57]
	v_mfma_f32_16x16x32_bf16 v[50:53], v[172:175], v[180:183], v[50:53]
	v_mfma_f32_16x16x32_bf16 v[38:41], v[158:161], v[188:191], v[38:41]
	v_mfma_f32_16x16x32_bf16 v[34:37], v[172:175], v[188:191], v[34:37]
	v_mfma_f32_16x16x32_bf16 v[22:25], v[158:161], v[196:199], v[22:25]
	v_mfma_f32_16x16x32_bf16 v[18:21], v[172:175], v[196:199], v[18:21]
	v_mfma_f32_16x16x32_bf16 v[6:9], v[158:161], v[204:207], v[6:9]
	v_mfma_f32_16x16x32_bf16 v[2:5], v[172:175], v[204:207], v[2:5]
	v_mfma_f32_16x16x32_bf16 v[54:57], v[168:171], v[184:187], v[54:57]
	v_mfma_f32_16x16x32_bf16 v[50:53], v[176:179], v[184:187], v[50:53]
	v_mfma_f32_16x16x32_bf16 v[38:41], v[168:171], v[192:195], v[38:41]
	v_mfma_f32_16x16x32_bf16 v[34:37], v[176:179], v[192:195], v[34:37]
	v_mfma_f32_16x16x32_bf16 v[22:25], v[168:171], v[200:203], v[22:25]
	v_mfma_f32_16x16x32_bf16 v[18:21], v[176:179], v[200:203], v[18:21]
	v_mfma_f32_16x16x32_bf16 v[6:9], v[168:171], v[208:211], v[6:9]
	v_mfma_f32_16x16x32_bf16 v[2:5], v[176:179], v[208:211], v[2:5]
	s_setprio 0
	s_barrier
	s_add_i32 s86, 0, 0x18000
	s_add_i32 s91, 0, 0x1c000
	v_add_u32_e32 v94, s86, v165
	v_add_u32_e32 v167, s91, v165
	ds_read_b128 v[74:77], v94
	ds_read_b128 v[78:81], v94 offset:1024
	ds_read_b128 v[90:93], v94 offset:2048
	ds_read_b128 v[94:97], v94 offset:3072
	ds_read_b128 v[158:161], v167
	ds_read_b128 v[168:171], v167 offset:1024
	ds_read_b128 v[172:175], v167 offset:2048
	ds_read_b128 v[176:179], v167 offset:3072
	s_add_u32 s44, s50, 0x40000
	s_addc_u32 s45, s51, 0
	s_mov_b32 m0, s53
	v_lshl_add_u64 v[218:219], s[44:45], 0, v[146:147]
	ds_read_b128 v[180:183], v166 offset:32768
	ds_read_b128 v[184:187], v166 offset:33792
	ds_read_b128 v[188:191], v166 offset:34816
	ds_read_b128 v[192:195], v166 offset:35840
	ds_read_b128 v[196:199], v166 offset:36864
	ds_read_b128 v[200:203], v166 offset:37888
	ds_read_b128 v[204:207], v166 offset:38912
	ds_read_b128 v[208:211], v166 offset:39936
	global_load_lds_dwordx4 v[218:219], off
	v_lshl_add_u64 v[218:219], s[44:45], 0, v[150:151]
	s_mov_b32 m0, s54
	s_nop 0
	global_load_lds_dwordx4 v[218:219], off
	s_waitcnt vmcnt(8)
	s_waitcnt lgkmcnt(0)
	s_barrier
	s_setprio 1
	s_waitcnt lgkmcnt(0)
	v_mfma_f32_16x16x32_bf16 v[142:145], v[74:77], v[180:183], v[142:145]
	v_mfma_f32_16x16x32_bf16 v[138:141], v[90:93], v[180:183], v[138:141]
	v_mfma_f32_16x16x32_bf16 v[126:129], v[74:77], v[188:191], v[126:129]
	v_mfma_f32_16x16x32_bf16 v[122:125], v[90:93], v[188:191], v[122:125]
	v_mfma_f32_16x16x32_bf16 v[110:113], v[74:77], v[196:199], v[110:113]
	v_mfma_f32_16x16x32_bf16 v[106:109], v[90:93], v[196:199], v[106:109]
	v_mfma_f32_16x16x32_bf16 v[86:89], v[74:77], v[204:207], v[86:89]
	v_mfma_f32_16x16x32_bf16 v[82:85], v[90:93], v[204:207], v[82:85]
	v_mfma_f32_16x16x32_bf16 v[142:145], v[78:81], v[184:187], v[142:145]
	v_mfma_f32_16x16x32_bf16 v[138:141], v[94:97], v[184:187], v[138:141]
	v_mfma_f32_16x16x32_bf16 v[126:129], v[78:81], v[192:195], v[126:129]
	v_mfma_f32_16x16x32_bf16 v[122:125], v[94:97], v[192:195], v[122:125]
	v_mfma_f32_16x16x32_bf16 v[110:113], v[78:81], v[200:203], v[110:113]
	v_mfma_f32_16x16x32_bf16 v[106:109], v[94:97], v[200:203], v[106:109]
	v_mfma_f32_16x16x32_bf16 v[86:89], v[78:81], v[208:211], v[86:89]
	v_mfma_f32_16x16x32_bf16 v[82:85], v[94:97], v[208:211], v[82:85]
	v_mfma_f32_16x16x32_bf16 v[134:137], v[158:161], v[180:183], v[134:137]
	v_mfma_f32_16x16x32_bf16 v[130:133], v[172:175], v[180:183], v[130:133]
	v_mfma_f32_16x16x32_bf16 v[118:121], v[158:161], v[188:191], v[118:121]
	v_mfma_f32_16x16x32_bf16 v[114:117], v[172:175], v[188:191], v[114:117]
	v_mfma_f32_16x16x32_bf16 v[102:105], v[158:161], v[196:199], v[102:105]
	v_mfma_f32_16x16x32_bf16 v[98:101], v[172:175], v[196:199], v[98:101]
	v_mfma_f32_16x16x32_bf16 v[70:73], v[158:161], v[204:207], v[70:73]
	v_mfma_f32_16x16x32_bf16 v[66:69], v[172:175], v[204:207], v[66:69]
	v_mfma_f32_16x16x32_bf16 v[134:137], v[168:171], v[184:187], v[134:137]
	v_mfma_f32_16x16x32_bf16 v[130:133], v[176:179], v[184:187], v[130:133]
	v_mfma_f32_16x16x32_bf16 v[118:121], v[168:171], v[192:195], v[118:121]
	v_mfma_f32_16x16x32_bf16 v[114:117], v[176:179], v[192:195], v[114:117]
	v_mfma_f32_16x16x32_bf16 v[102:105], v[168:171], v[200:203], v[102:105]
	v_mfma_f32_16x16x32_bf16 v[98:101], v[176:179], v[200:203], v[98:101]
	v_mfma_f32_16x16x32_bf16 v[70:73], v[168:171], v[208:211], v[70:73]
	v_mfma_f32_16x16x32_bf16 v[66:69], v[176:179], v[208:211], v[66:69]
	s_setprio 0
	s_barrier
	s_add_i32 s44, s86, s36
	v_lshl_add_u64 v[162:163], v[162:163], 0, s[42:43]
	s_mov_b32 m0, s44
	ds_read_b128 v[180:183], v166 offset:49152
	ds_read_b128 v[184:187], v166 offset:50176
	ds_read_b128 v[188:191], v166 offset:51200
	ds_read_b128 v[192:195], v166 offset:52224
	ds_read_b128 v[196:199], v166 offset:53248
	ds_read_b128 v[200:203], v166 offset:54272
	ds_read_b128 v[204:207], v166 offset:55296
	ds_read_b128 v[208:211], v166 offset:56320
	global_load_lds_dwordx4 v[162:163], off
	s_add_i32 m0, s44, 0x2000
	s_add_u32 s44, s48, 0x40080
	v_lshl_add_u64 v[162:163], v[212:213], 0, s[42:43]
	s_addc_u32 s45, s49, 0
	s_add_i32 s48, s91, s36
	global_load_lds_dwordx4 v[162:163], off
	v_lshl_add_u64 v[162:163], s[44:45], 0, v[148:149]
	s_mov_b32 m0, s48
	s_nop 0
	global_load_lds_dwordx4 v[162:163], off
	v_lshl_add_u64 v[162:163], s[44:45], 0, v[152:153]
	s_add_i32 m0, s48, 0x2000
	s_nop 0
	global_load_lds_dwordx4 v[162:163], off
	v_lshl_add_u64 v[162:163], v[214:215], 0, s[42:43]
	s_mov_b32 m0, s61
	s_nop 0
	global_load_lds_dwordx4 v[162:163], off
	v_lshl_add_u64 v[162:163], v[216:217], 0, s[42:43]
	s_mov_b32 m0, s64
	s_nop 0
	global_load_lds_dwordx4 v[162:163], off
	s_waitcnt vmcnt(8)
	s_waitcnt lgkmcnt(0)
	s_barrier
	s_setprio 1
	s_waitcnt lgkmcnt(0)
	v_mfma_f32_16x16x32_bf16 v[62:65], v[74:77], v[180:183], v[62:65]
	v_mfma_f32_16x16x32_bf16 v[58:61], v[90:93], v[180:183], v[58:61]
	v_mfma_f32_16x16x32_bf16 v[46:49], v[74:77], v[188:191], v[46:49]
	v_mfma_f32_16x16x32_bf16 v[42:45], v[90:93], v[188:191], v[42:45]
	v_mfma_f32_16x16x32_bf16 v[30:33], v[74:77], v[196:199], v[30:33]
	v_mfma_f32_16x16x32_bf16 v[26:29], v[90:93], v[196:199], v[26:29]
	v_mfma_f32_16x16x32_bf16 v[14:17], v[74:77], v[204:207], v[14:17]
	v_mfma_f32_16x16x32_bf16 v[10:13], v[90:93], v[204:207], v[10:13]
	v_mfma_f32_16x16x32_bf16 v[62:65], v[78:81], v[184:187], v[62:65]
	v_mfma_f32_16x16x32_bf16 v[58:61], v[94:97], v[184:187], v[58:61]
	v_mfma_f32_16x16x32_bf16 v[46:49], v[78:81], v[192:195], v[46:49]
	v_mfma_f32_16x16x32_bf16 v[42:45], v[94:97], v[192:195], v[42:45]
	v_mfma_f32_16x16x32_bf16 v[30:33], v[78:81], v[200:203], v[30:33]
	v_mfma_f32_16x16x32_bf16 v[26:29], v[94:97], v[200:203], v[26:29]
	v_mfma_f32_16x16x32_bf16 v[14:17], v[78:81], v[208:211], v[14:17]
	v_mfma_f32_16x16x32_bf16 v[10:13], v[94:97], v[208:211], v[10:13]
	v_mfma_f32_16x16x32_bf16 v[54:57], v[158:161], v[180:183], v[54:57]
	v_mfma_f32_16x16x32_bf16 v[50:53], v[172:175], v[180:183], v[50:53]
	v_mfma_f32_16x16x32_bf16 v[38:41], v[158:161], v[188:191], v[38:41]
	v_mfma_f32_16x16x32_bf16 v[34:37], v[172:175], v[188:191], v[34:37]
	v_mfma_f32_16x16x32_bf16 v[22:25], v[158:161], v[196:199], v[22:25]
	v_mfma_f32_16x16x32_bf16 v[18:21], v[172:175], v[196:199], v[18:21]
	v_mfma_f32_16x16x32_bf16 v[6:9], v[158:161], v[204:207], v[6:9]
	v_mfma_f32_16x16x32_bf16 v[2:5], v[172:175], v[204:207], v[2:5]
	v_mfma_f32_16x16x32_bf16 v[54:57], v[168:171], v[184:187], v[54:57]
	v_mfma_f32_16x16x32_bf16 v[50:53], v[176:179], v[184:187], v[50:53]
	v_mfma_f32_16x16x32_bf16 v[38:41], v[168:171], v[192:195], v[38:41]
	v_mfma_f32_16x16x32_bf16 v[34:37], v[176:179], v[192:195], v[34:37]
	v_mfma_f32_16x16x32_bf16 v[22:25], v[168:171], v[200:203], v[22:25]
	v_mfma_f32_16x16x32_bf16 v[18:21], v[176:179], v[200:203], v[18:21]
	v_mfma_f32_16x16x32_bf16 v[6:9], v[168:171], v[208:211], v[6:9]
	v_mfma_f32_16x16x32_bf16 v[2:5], v[176:179], v[208:211], v[2:5]
	s_setprio 0
	s_barrier
	s_add_i32 s90, s90, 2
	s_add_u32 s56, s56, 0x100
	s_addc_u32 s89, s89, 0
	s_cmp_gt_u32 s90, 13
	s_mov_b64 s[44:45], s[46:47]
	s_cbranch_scc0 .LBB0_206
	s_and_b64 vcc, exec, s[14:15]
	s_cbranch_vccz .LBB0_209
	s_barrier

.LBB0_255:
	s_add_u32 s22, s18, s20
	s_addc_u32 s23, s19, s21
	s_add_u32 s22, s22, 0x100
	s_addc_u32 s23, s23, 0
	s_add_u32 s36, s57, s20
	s_addc_u32 s38, s34, s21
	s_add_i32 s39, 0, 0x10000
	s_cmpk_eq_i32 s20, 0xb00
	s_cselect_b32 s27, s7, s23
	s_cselect_b32 s26, s6, s22
	v_add_u32_e32 v157, s39, v155
	s_cselect_b32 s23, s17, s38
	s_cselect_b32 s22, s16, s36
	s_add_i32 s36, 0, 0x14000
	ds_read_b128 v[130:133], v157
	ds_read_b128 v[134:137], v157 offset:1024
	ds_read_b128 v[158:161], v157 offset:2048
	ds_read_b128 v[162:165], v157 offset:3072
	v_add_u32_e32 v157, s36, v155
	ds_read_b128 v[166:169], v157
	ds_read_b128 v[170:173], v157 offset:1024
	ds_read_b128 v[174:177], v157 offset:2048
	ds_read_b128 v[178:181], v157 offset:3072
	v_lshl_add_u64 v[210:211], v[150:151], 0, s[20:21]
	s_add_i32 m0, s50, 0xc000
	ds_read_b128 v[182:185], v156
	ds_read_b128 v[186:189], v156 offset:1024
	ds_read_b128 v[190:193], v156 offset:2048
	ds_read_b128 v[194:197], v156 offset:3072
	ds_read_b128 v[198:201], v156 offset:4096
	ds_read_b128 v[202:205], v156 offset:5120
	ds_read_b128 v[206:209], v156 offset:6144
	ds_read_b128 v[214:217], v156 offset:7168
	global_load_lds_dwordx4 v[210:211], off
	v_lshl_add_u64 v[210:211], v[152:153], 0, s[20:21]
	s_add_i32 m0, s50, 0xe000
	s_nop 0
	global_load_lds_dwordx4 v[210:211], off
	s_waitcnt vmcnt(8)
	s_waitcnt lgkmcnt(0)
	s_barrier
	s_setprio 1
	s_waitcnt lgkmcnt(0)
	v_mfma_f32_16x16x32_bf16 v[126:129], v[130:133], v[182:185], v[126:129]
	v_mfma_f32_16x16x32_bf16 v[122:125], v[158:161], v[182:185], v[122:125]
	v_mfma_f32_16x16x32_bf16 v[110:113], v[130:133], v[190:193], v[110:113]
	v_mfma_f32_16x16x32_bf16 v[106:109], v[158:161], v[190:193], v[106:109]
	v_mfma_f32_16x16x32_bf16 v[94:97], v[130:133], v[198:201], v[94:97]
	v_mfma_f32_16x16x32_bf16 v[90:93], v[158:161], v[198:201], v[90:93]
	v_mfma_f32_16x16x32_bf16 v[78:81], v[130:133], v[206:209], v[78:81]
	v_mfma_f32_16x16x32_bf16 v[74:77], v[158:161], v[206:209], v[74:77]
	v_mfma_f32_16x16x32_bf16 v[126:129], v[134:137], v[186:189], v[126:129]
	v_mfma_f32_16x16x32_bf16 v[122:125], v[162:165], v[186:189], v[122:125]
	v_mfma_f32_16x16x32_bf16 v[110:113], v[134:137], v[194:197], v[110:113]
	v_mfma_f32_16x16x32_bf16 v[106:109], v[162:165], v[194:197], v[106:109]
	v_mfma_f32_16x16x32_bf16 v[94:97], v[134:137], v[202:205], v[94:97]
	v_mfma_f32_16x16x32_bf16 v[90:93], v[162:165], v[202:205], v[90:93]
	v_mfma_f32_16x16x32_bf16 v[78:81], v[134:137], v[214:217], v[78:81]
	v_mfma_f32_16x16x32_bf16 v[74:77], v[162:165], v[214:217], v[74:77]
	v_mfma_f32_16x16x32_bf16 v[118:121], v[166:169], v[182:185], v[118:121]
	v_mfma_f32_16x16x32_bf16 v[114:117], v[174:177], v[182:185], v[114:117]
	v_mfma_f32_16x16x32_bf16 v[102:105], v[166:169], v[190:193], v[102:105]
	v_mfma_f32_16x16x32_bf16 v[98:101], v[174:177], v[190:193], v[98:101]
	v_mfma_f32_16x16x32_bf16 v[86:89], v[166:169], v[198:201], v[86:89]
	v_mfma_f32_16x16x32_bf16 v[82:85], v[174:177], v[198:201], v[82:85]
	v_mfma_f32_16x16x32_bf16 v[70:73], v[166:169], v[206:209], v[70:73]
	v_mfma_f32_16x16x32_bf16 v[66:69], v[174:177], v[206:209], v[66:69]
	v_mfma_f32_16x16x32_bf16 v[118:121], v[170:173], v[186:189], v[118:121]
	v_mfma_f32_16x16x32_bf16 v[114:117], v[178:181], v[186:189], v[114:117]
	v_mfma_f32_16x16x32_bf16 v[102:105], v[170:173], v[194:197], v[102:105]
	v_mfma_f32_16x16x32_bf16 v[98:101], v[178:181], v[194:197], v[98:101]
	v_mfma_f32_16x16x32_bf16 v[86:89], v[170:173], v[202:205], v[86:89]
	v_mfma_f32_16x16x32_bf16 v[82:85], v[178:181], v[202:205], v[82:85]
	v_mfma_f32_16x16x32_bf16 v[70:73], v[170:173], v[214:217], v[70:73]
	v_mfma_f32_16x16x32_bf16 v[66:69], v[178:181], v[214:217], v[66:69]
	s_setprio 0
	s_barrier
	s_add_i32 s38, s39, s49
	v_lshl_add_u64 v[210:211], s[22:23], 0, v[140:141]
	s_mov_b32 m0, s38
	ds_read_b128 v[182:185], v156 offset:16384
	ds_read_b128 v[186:189], v156 offset:17408
	ds_read_b128 v[190:193], v156 offset:18432
	ds_read_b128 v[194:197], v156 offset:19456
	ds_read_b128 v[198:201], v156 offset:20480
	ds_read_b128 v[202:205], v156 offset:21504
	ds_read_b128 v[206:209], v156 offset:22528
	ds_read_b128 v[214:217], v156 offset:23552
	global_load_lds_dwordx4 v[210:211], off
	s_add_i32 m0, s38, 0x2000
	s_add_u32 s38, s22, 0x60000
	v_lshl_add_u64 v[212:213], s[22:23], 0, v[144:145]
	s_addc_u32 s39, s23, 0
	s_add_i32 s36, s36, s49
	global_load_lds_dwordx4 v[212:213], off
	v_lshl_add_u64 v[218:219], s[38:39], 0, v[140:141]
	s_mov_b32 m0, s36
	v_lshl_add_u64 v[220:221], s[26:27], 0, v[142:143]
	global_load_lds_dwordx4 v[218:219], off
	v_lshl_add_u64 v[218:219], s[38:39], 0, v[144:145]
	s_add_i32 m0, s36, 0x2000
	s_nop 0
	global_load_lds_dwordx4 v[218:219], off
	v_lshl_add_u64 v[218:219], s[26:27], 0, v[138:139]
	s_mov_b32 m0, s50
	s_nop 0
	global_load_lds_dwordx4 v[218:219], off
	s_mov_b32 m0, s51
	s_nop 0
	global_load_lds_dwordx4 v[220:221], off
	s_waitcnt vmcnt(8)
	s_waitcnt lgkmcnt(0)
	s_barrier
	s_setprio 1
	s_waitcnt lgkmcnt(0)
	v_mfma_f32_16x16x32_bf16 v[62:65], v[130:133], v[182:185], v[62:65]
	v_mfma_f32_16x16x32_bf16 v[58:61], v[158:161], v[182:185], v[58:61]
	v_mfma_f32_16x16x32_bf16 v[46:49], v[130:133], v[190:193], v[46:49]
	v_mfma_f32_16x16x32_bf16 v[42:45], v[158:161], v[190:193], v[42:45]
	v_mfma_f32_16x16x32_bf16 v[30:33], v[130:133], v[198:201], v[30:33]
	v_mfma_f32_16x16x32_bf16 v[26:29], v[158:161], v[198:201], v[26:29]
	v_mfma_f32_16x16x32_bf16 v[14:17], v[130:133], v[206:209], v[14:17]
	v_mfma_f32_16x16x32_bf16 v[10:13], v[158:161], v[206:209], v[10:13]
	v_mfma_f32_16x16x32_bf16 v[62:65], v[134:137], v[186:189], v[62:65]
	v_mfma_f32_16x16x32_bf16 v[58:61], v[162:165], v[186:189], v[58:61]
	v_mfma_f32_16x16x32_bf16 v[46:49], v[134:137], v[194:197], v[46:49]
	v_mfma_f32_16x16x32_bf16 v[42:45], v[162:165], v[194:197], v[42:45]
	v_mfma_f32_16x16x32_bf16 v[30:33], v[134:137], v[202:205], v[30:33]
	v_mfma_f32_16x16x32_bf16 v[26:29], v[162:165], v[202:205], v[26:29]
	v_mfma_f32_16x16x32_bf16 v[14:17], v[134:137], v[214:217], v[14:17]
	v_mfma_f32_16x16x32_bf16 v[10:13], v[162:165], v[214:217], v[10:13]
	v_mfma_f32_16x16x32_bf16 v[54:57], v[166:169], v[182:185], v[54:57]
	v_mfma_f32_16x16x32_bf16 v[50:53], v[174:177], v[182:185], v[50:53]
	v_mfma_f32_16x16x32_bf16 v[38:41], v[166:169], v[190:193], v[38:41]
	v_mfma_f32_16x16x32_bf16 v[34:37], v[174:177], v[190:193], v[34:37]
	v_mfma_f32_16x16x32_bf16 v[22:25], v[166:169], v[198:201], v[22:25]
	v_mfma_f32_16x16x32_bf16 v[18:21], v[174:177], v[198:201], v[18:21]
	v_mfma_f32_16x16x32_bf16 v[6:9], v[166:169], v[206:209], v[6:9]
	v_mfma_f32_16x16x32_bf16 v[2:5], v[174:177], v[206:209], v[2:5]
	v_mfma_f32_16x16x32_bf16 v[54:57], v[170:173], v[186:189], v[54:57]
	v_mfma_f32_16x16x32_bf16 v[50:53], v[178:181], v[186:189], v[50:53]
	v_mfma_f32_16x16x32_bf16 v[38:41], v[170:173], v[194:197], v[38:41]
	v_mfma_f32_16x16x32_bf16 v[34:37], v[178:181], v[194:197], v[34:37]
	v_mfma_f32_16x16x32_bf16 v[22:25], v[170:173], v[202:205], v[22:25]
	v_mfma_f32_16x16x32_bf16 v[18:21], v[178:181], v[202:205], v[18:21]
	v_mfma_f32_16x16x32_bf16 v[6:9], v[170:173], v[214:217], v[6:9]
	v_mfma_f32_16x16x32_bf16 v[2:5], v[178:181], v[214:217], v[2:5]
	s_setprio 0
	s_barrier
	s_add_i32 s36, 0, 0x18000
	v_add_u32_e32 v157, s36, v155
	s_add_i32 s38, 0, 0x1c000
	ds_read_b128 v[130:133], v157
	ds_read_b128 v[134:137], v157 offset:1024
	ds_read_b128 v[158:161], v157 offset:2048
	ds_read_b128 v[162:165], v157 offset:3072
	v_add_u32_e32 v157, s38, v155
	ds_read_b128 v[166:169], v157
	ds_read_b128 v[170:173], v157 offset:1024
	ds_read_b128 v[174:177], v157 offset:2048
	ds_read_b128 v[178:181], v157 offset:3072
	s_add_u32 s26, s26, 0x60000
	s_addc_u32 s27, s27, 0
	s_mov_b32 m0, s60
	v_lshl_add_u64 v[222:223], s[26:27], 0, v[138:139]
	ds_read_b128 v[182:185], v156 offset:32768
	ds_read_b128 v[186:189], v156 offset:33792
	ds_read_b128 v[190:193], v156 offset:34816
	ds_read_b128 v[194:197], v156 offset:35840
	ds_read_b128 v[198:201], v156 offset:36864
	ds_read_b128 v[202:205], v156 offset:37888
	ds_read_b128 v[206:209], v156 offset:38912
	ds_read_b128 v[214:217], v156 offset:39936
	global_load_lds_dwordx4 v[222:223], off
	v_lshl_add_u64 v[222:223], s[26:27], 0, v[142:143]
	s_mov_b32 m0, s61
	s_nop 0
	global_load_lds_dwordx4 v[222:223], off
	s_waitcnt vmcnt(8)
	s_waitcnt lgkmcnt(0)
	s_barrier
	s_setprio 1
	s_waitcnt lgkmcnt(0)
	v_mfma_f32_16x16x32_bf16 v[126:129], v[130:133], v[182:185], v[126:129]
	v_mfma_f32_16x16x32_bf16 v[122:125], v[158:161], v[182:185], v[122:125]
	v_mfma_f32_16x16x32_bf16 v[110:113], v[130:133], v[190:193], v[110:113]
	v_mfma_f32_16x16x32_bf16 v[106:109], v[158:161], v[190:193], v[106:109]
	v_mfma_f32_16x16x32_bf16 v[94:97], v[130:133], v[198:201], v[94:97]
	v_mfma_f32_16x16x32_bf16 v[90:93], v[158:161], v[198:201], v[90:93]
	v_mfma_f32_16x16x32_bf16 v[78:81], v[130:133], v[206:209], v[78:81]
	v_mfma_f32_16x16x32_bf16 v[74:77], v[158:161], v[206:209], v[74:77]
	v_mfma_f32_16x16x32_bf16 v[126:129], v[134:137], v[186:189], v[126:129]
	v_mfma_f32_16x16x32_bf16 v[122:125], v[162:165], v[186:189], v[122:125]
	v_mfma_f32_16x16x32_bf16 v[110:113], v[134:137], v[194:197], v[110:113]
	v_mfma_f32_16x16x32_bf16 v[106:109], v[162:165], v[194:197], v[106:109]
	v_mfma_f32_16x16x32_bf16 v[94:97], v[134:137], v[202:205], v[94:97]
	v_mfma_f32_16x16x32_bf16 v[90:93], v[162:165], v[202:205], v[90:93]
	v_mfma_f32_16x16x32_bf16 v[78:81], v[134:137], v[214:217], v[78:81]
	v_mfma_f32_16x16x32_bf16 v[74:77], v[162:165], v[214:217], v[74:77]
	v_mfma_f32_16x16x32_bf16 v[118:121], v[166:169], v[182:185], v[118:121]
	v_mfma_f32_16x16x32_bf16 v[114:117], v[174:177], v[182:185], v[114:117]
	v_mfma_f32_16x16x32_bf16 v[102:105], v[166:169], v[190:193], v[102:105]
	v_mfma_f32_16x16x32_bf16 v[98:101], v[174:177], v[190:193], v[98:101]
	v_mfma_f32_16x16x32_bf16 v[86:89], v[166:169], v[198:201], v[86:89]
	v_mfma_f32_16x16x32_bf16 v[82:85], v[174:177], v[198:201], v[82:85]
	v_mfma_f32_16x16x32_bf16 v[70:73], v[166:169], v[206:209], v[70:73]
	v_mfma_f32_16x16x32_bf16 v[66:69], v[174:177], v[206:209], v[66:69]
	v_mfma_f32_16x16x32_bf16 v[118:121], v[170:173], v[186:189], v[118:121]
	v_mfma_f32_16x16x32_bf16 v[114:117], v[178:181], v[186:189], v[114:117]
	v_mfma_f32_16x16x32_bf16 v[102:105], v[170:173], v[194:197], v[102:105]
	v_mfma_f32_16x16x32_bf16 v[98:101], v[178:181], v[194:197], v[98:101]
	v_mfma_f32_16x16x32_bf16 v[86:89], v[170:173], v[202:205], v[86:89]
	v_mfma_f32_16x16x32_bf16 v[82:85], v[178:181], v[202:205], v[82:85]
	v_mfma_f32_16x16x32_bf16 v[70:73], v[170:173], v[214:217], v[70:73]
	v_mfma_f32_16x16x32_bf16 v[66:69], v[178:181], v[214:217], v[66:69]
	s_setprio 0
	s_barrier
	s_add_i32 s26, s36, s49
	v_lshl_add_u64 v[210:211], v[210:211], 0, s[42:43]
	s_mov_b32 m0, s26
	ds_read_b128 v[182:185], v156 offset:49152
	ds_read_b128 v[186:189], v156 offset:50176
	ds_read_b128 v[190:193], v156 offset:51200
	ds_read_b128 v[194:197], v156 offset:52224
	ds_read_b128 v[198:201], v156 offset:53248
	ds_read_b128 v[202:205], v156 offset:54272
	ds_read_b128 v[206:209], v156 offset:55296
	ds_read_b128 v[214:217], v156 offset:56320
	global_load_lds_dwordx4 v[210:211], off
	s_add_i32 m0, s26, 0x2000
	s_add_u32 s22, s22, 0x60080
	v_lshl_add_u64 v[210:211], v[212:213], 0, s[42:43]
	s_addc_u32 s23, s23, 0
	s_add_i32 s26, s38, s49
	global_load_lds_dwordx4 v[210:211], off
	v_lshl_add_u64 v[210:211], s[22:23], 0, v[140:141]
	s_mov_b32 m0, s26
	s_nop 0
	global_load_lds_dwordx4 v[210:211], off
	v_lshl_add_u64 v[210:211], s[22:23], 0, v[144:145]
	s_add_i32 m0, s26, 0x2000
	s_nop 0
	global_load_lds_dwordx4 v[210:211], off
	v_lshl_add_u64 v[210:211], v[218:219], 0, s[42:43]
	s_mov_b32 m0, s66
	s_nop 0
	global_load_lds_dwordx4 v[210:211], off
	v_lshl_add_u64 v[210:211], v[220:221], 0, s[42:43]
	s_mov_b32 m0, s67
	s_nop 0
	global_load_lds_dwordx4 v[210:211], off
	s_waitcnt vmcnt(8)
	s_waitcnt lgkmcnt(0)
	s_barrier
	s_setprio 1
	s_waitcnt lgkmcnt(0)
	v_mfma_f32_16x16x32_bf16 v[62:65], v[130:133], v[182:185], v[62:65]
	v_mfma_f32_16x16x32_bf16 v[58:61], v[158:161], v[182:185], v[58:61]
	v_mfma_f32_16x16x32_bf16 v[46:49], v[130:133], v[190:193], v[46:49]
	v_mfma_f32_16x16x32_bf16 v[42:45], v[158:161], v[190:193], v[42:45]
	v_mfma_f32_16x16x32_bf16 v[30:33], v[130:133], v[198:201], v[30:33]
	v_mfma_f32_16x16x32_bf16 v[26:29], v[158:161], v[198:201], v[26:29]
	v_mfma_f32_16x16x32_bf16 v[14:17], v[130:133], v[206:209], v[14:17]
	v_mfma_f32_16x16x32_bf16 v[10:13], v[158:161], v[206:209], v[10:13]
	v_mfma_f32_16x16x32_bf16 v[62:65], v[134:137], v[186:189], v[62:65]
	v_mfma_f32_16x16x32_bf16 v[58:61], v[162:165], v[186:189], v[58:61]
	v_mfma_f32_16x16x32_bf16 v[46:49], v[134:137], v[194:197], v[46:49]
	v_mfma_f32_16x16x32_bf16 v[42:45], v[162:165], v[194:197], v[42:45]
	v_mfma_f32_16x16x32_bf16 v[30:33], v[134:137], v[202:205], v[30:33]
	v_mfma_f32_16x16x32_bf16 v[26:29], v[162:165], v[202:205], v[26:29]
	v_mfma_f32_16x16x32_bf16 v[14:17], v[134:137], v[214:217], v[14:17]
	v_mfma_f32_16x16x32_bf16 v[10:13], v[162:165], v[214:217], v[10:13]
	v_mfma_f32_16x16x32_bf16 v[54:57], v[166:169], v[182:185], v[54:57]
	v_mfma_f32_16x16x32_bf16 v[50:53], v[174:177], v[182:185], v[50:53]
	v_mfma_f32_16x16x32_bf16 v[38:41], v[166:169], v[190:193], v[38:41]
	v_mfma_f32_16x16x32_bf16 v[34:37], v[174:177], v[190:193], v[34:37]
	v_mfma_f32_16x16x32_bf16 v[22:25], v[166:169], v[198:201], v[22:25]
	v_mfma_f32_16x16x32_bf16 v[18:21], v[174:177], v[198:201], v[18:21]
	v_mfma_f32_16x16x32_bf16 v[6:9], v[166:169], v[206:209], v[6:9]
	v_mfma_f32_16x16x32_bf16 v[2:5], v[174:177], v[206:209], v[2:5]
	v_mfma_f32_16x16x32_bf16 v[54:57], v[170:173], v[186:189], v[54:57]
	v_mfma_f32_16x16x32_bf16 v[50:53], v[178:181], v[186:189], v[50:53]
	v_mfma_f32_16x16x32_bf16 v[38:41], v[170:173], v[194:197], v[38:41]
	v_mfma_f32_16x16x32_bf16 v[34:37], v[178:181], v[194:197], v[34:37]
	v_mfma_f32_16x16x32_bf16 v[22:25], v[170:173], v[202:205], v[22:25]
	v_mfma_f32_16x16x32_bf16 v[18:21], v[178:181], v[202:205], v[18:21]
	v_mfma_f32_16x16x32_bf16 v[6:9], v[170:173], v[214:217], v[6:9]
	v_mfma_f32_16x16x32_bf16 v[2:5], v[178:181], v[214:217], v[2:5]
	s_setprio 0
	s_barrier
	s_add_i32 s22, s35, 2
	s_add_u32 s20, s20, 0x100
	s_addc_u32 s21, s21, 0
	s_cmp_gt_u32 s35, 21
	s_mov_b32 s35, s22
	s_cbranch_scc1 .LBB0_264

.LBB0_292:
	s_add_u32 s46, s44, 0x100
	s_addc_u32 s47, s45, 0
	s_add_i32 s39, 0, 0x10000
	s_cmp_eq_u32 s37, 4
	s_cselect_b32 s51, s1, s47
	s_cselect_b32 s50, s21, s46
	v_add_u32_e32 v146, s39, v149
	s_cselect_b32 s49, s19, s36
	s_cselect_b32 s48, s34, s35
	s_add_i32 s52, 0, 0x14000
	ds_read_b128 v[142:145], v146
	ds_read_b128 v[152:155], v146 offset:1024
	ds_read_b128 v[156:159], v146 offset:2048
	ds_read_b128 v[160:163], v146 offset:3072
	v_add_u32_e32 v146, s52, v149
	ds_read_b128 v[164:167], v146
	ds_read_b128 v[168:171], v146 offset:1024
	ds_read_b128 v[172:175], v146 offset:2048
	ds_read_b128 v[176:179], v146 offset:3072
	v_lshl_add_u64 v[146:147], s[44:45], 0, v[138:139]
	s_add_i32 m0, s65, 0xc000
	ds_read_b128 v[180:183], v150
	ds_read_b128 v[184:187], v150 offset:1024
	ds_read_b128 v[188:191], v150 offset:2048
	ds_read_b128 v[192:195], v150 offset:3072
	ds_read_b128 v[196:199], v150 offset:4096
	ds_read_b128 v[200:203], v150 offset:5120
	ds_read_b128 v[204:207], v150 offset:6144
	ds_read_b128 v[208:211], v150 offset:7168
	global_load_lds_dwordx4 v[146:147], off
	v_lshl_add_u64 v[146:147], s[44:45], 0, v[140:141]
	s_add_i32 m0, s65, 0xe000
	s_nop 0
	global_load_lds_dwordx4 v[146:147], off
	s_waitcnt vmcnt(8)
	s_waitcnt lgkmcnt(0)
	s_barrier
	s_setprio 1
	s_waitcnt lgkmcnt(0)
	v_mfma_f32_16x16x32_bf16 v[126:129], v[142:145], v[180:183], v[126:129]
	v_mfma_f32_16x16x32_bf16 v[122:125], v[156:159], v[180:183], v[122:125]
	v_mfma_f32_16x16x32_bf16 v[110:113], v[142:145], v[188:191], v[110:113]
	v_mfma_f32_16x16x32_bf16 v[106:109], v[156:159], v[188:191], v[106:109]
	v_mfma_f32_16x16x32_bf16 v[94:97], v[142:145], v[196:199], v[94:97]
	v_mfma_f32_16x16x32_bf16 v[90:93], v[156:159], v[196:199], v[90:93]
	v_mfma_f32_16x16x32_bf16 v[78:81], v[142:145], v[204:207], v[78:81]
	v_mfma_f32_16x16x32_bf16 v[74:77], v[156:159], v[204:207], v[74:77]
	v_mfma_f32_16x16x32_bf16 v[126:129], v[152:155], v[184:187], v[126:129]
	v_mfma_f32_16x16x32_bf16 v[122:125], v[160:163], v[184:187], v[122:125]
	v_mfma_f32_16x16x32_bf16 v[110:113], v[152:155], v[192:195], v[110:113]
	v_mfma_f32_16x16x32_bf16 v[106:109], v[160:163], v[192:195], v[106:109]
	v_mfma_f32_16x16x32_bf16 v[94:97], v[152:155], v[200:203], v[94:97]
	v_mfma_f32_16x16x32_bf16 v[90:93], v[160:163], v[200:203], v[90:93]
	v_mfma_f32_16x16x32_bf16 v[78:81], v[152:155], v[208:211], v[78:81]
	v_mfma_f32_16x16x32_bf16 v[74:77], v[160:163], v[208:211], v[74:77]
	v_mfma_f32_16x16x32_bf16 v[118:121], v[164:167], v[180:183], v[118:121]
	v_mfma_f32_16x16x32_bf16 v[114:117], v[172:175], v[180:183], v[114:117]
	v_mfma_f32_16x16x32_bf16 v[102:105], v[164:167], v[188:191], v[102:105]
	v_mfma_f32_16x16x32_bf16 v[98:101], v[172:175], v[188:191], v[98:101]
	v_mfma_f32_16x16x32_bf16 v[86:89], v[164:167], v[196:199], v[86:89]
	v_mfma_f32_16x16x32_bf16 v[82:85], v[172:175], v[196:199], v[82:85]
	v_mfma_f32_16x16x32_bf16 v[70:73], v[164:167], v[204:207], v[70:73]
	v_mfma_f32_16x16x32_bf16 v[66:69], v[172:175], v[204:207], v[66:69]
	v_mfma_f32_16x16x32_bf16 v[118:121], v[168:171], v[184:187], v[118:121]
	v_mfma_f32_16x16x32_bf16 v[114:117], v[176:179], v[184:187], v[114:117]
	v_mfma_f32_16x16x32_bf16 v[102:105], v[168:171], v[192:195], v[102:105]
	v_mfma_f32_16x16x32_bf16 v[98:101], v[176:179], v[192:195], v[98:101]
	v_mfma_f32_16x16x32_bf16 v[86:89], v[168:171], v[200:203], v[86:89]
	v_mfma_f32_16x16x32_bf16 v[82:85], v[176:179], v[200:203], v[82:85]
	v_mfma_f32_16x16x32_bf16 v[70:73], v[168:171], v[208:211], v[70:73]
	v_mfma_f32_16x16x32_bf16 v[66:69], v[176:179], v[208:211], v[66:69]
	s_setprio 0
	s_barrier
	s_add_i32 s39, s39, s64
	v_lshl_add_u64 v[146:147], s[48:49], 0, v[132:133]
	s_mov_b32 m0, s39
	ds_read_b128 v[180:183], v150 offset:16384
	ds_read_b128 v[184:187], v150 offset:17408
	ds_read_b128 v[188:191], v150 offset:18432
	ds_read_b128 v[192:195], v150 offset:19456
	ds_read_b128 v[196:199], v150 offset:20480
	ds_read_b128 v[200:203], v150 offset:21504
	ds_read_b128 v[204:207], v150 offset:22528
	ds_read_b128 v[208:211], v150 offset:23552
	global_load_lds_dwordx4 v[146:147], off
	s_add_i32 m0, s39, 0x2000
	s_add_u32 s44, s48, 0x20000
	v_lshl_add_u64 v[212:213], s[48:49], 0, v[136:137]
	s_addc_u32 s45, s49, 0
	s_add_i32 s39, s52, s64
	global_load_lds_dwordx4 v[212:213], off
	v_lshl_add_u64 v[214:215], s[44:45], 0, v[132:133]
	s_mov_b32 m0, s39
	v_lshl_add_u64 v[216:217], s[50:51], 0, v[134:135]
	global_load_lds_dwordx4 v[214:215], off
	v_lshl_add_u64 v[214:215], s[44:45], 0, v[136:137]
	s_add_i32 m0, s39, 0x2000
	s_nop 0
	global_load_lds_dwordx4 v[214:215], off
	v_lshl_add_u64 v[214:215], s[50:51], 0, v[130:131]
	s_mov_b32 m0, s65
	s_nop 0
	global_load_lds_dwordx4 v[214:215], off
	s_mov_b32 m0, s66
	s_nop 0
	global_load_lds_dwordx4 v[216:217], off
	s_waitcnt vmcnt(8)
	s_waitcnt lgkmcnt(0)
	s_barrier
	s_setprio 1
	s_waitcnt lgkmcnt(0)
	v_mfma_f32_16x16x32_bf16 v[62:65], v[142:145], v[180:183], v[62:65]
	v_mfma_f32_16x16x32_bf16 v[58:61], v[156:159], v[180:183], v[58:61]
	v_mfma_f32_16x16x32_bf16 v[46:49], v[142:145], v[188:191], v[46:49]
	v_mfma_f32_16x16x32_bf16 v[42:45], v[156:159], v[188:191], v[42:45]
	v_mfma_f32_16x16x32_bf16 v[30:33], v[142:145], v[196:199], v[30:33]
	v_mfma_f32_16x16x32_bf16 v[26:29], v[156:159], v[196:199], v[26:29]
	v_mfma_f32_16x16x32_bf16 v[14:17], v[142:145], v[204:207], v[14:17]
	v_mfma_f32_16x16x32_bf16 v[10:13], v[156:159], v[204:207], v[10:13]
	v_mfma_f32_16x16x32_bf16 v[62:65], v[152:155], v[184:187], v[62:65]
	v_mfma_f32_16x16x32_bf16 v[58:61], v[160:163], v[184:187], v[58:61]
	v_mfma_f32_16x16x32_bf16 v[46:49], v[152:155], v[192:195], v[46:49]
	v_mfma_f32_16x16x32_bf16 v[42:45], v[160:163], v[192:195], v[42:45]
	v_mfma_f32_16x16x32_bf16 v[30:33], v[152:155], v[200:203], v[30:33]
	v_mfma_f32_16x16x32_bf16 v[26:29], v[160:163], v[200:203], v[26:29]
	v_mfma_f32_16x16x32_bf16 v[14:17], v[152:155], v[208:211], v[14:17]
	v_mfma_f32_16x16x32_bf16 v[10:13], v[160:163], v[208:211], v[10:13]
	v_mfma_f32_16x16x32_bf16 v[54:57], v[164:167], v[180:183], v[54:57]
	v_mfma_f32_16x16x32_bf16 v[50:53], v[172:175], v[180:183], v[50:53]
	v_mfma_f32_16x16x32_bf16 v[38:41], v[164:167], v[188:191], v[38:41]
	v_mfma_f32_16x16x32_bf16 v[34:37], v[172:175], v[188:191], v[34:37]
	v_mfma_f32_16x16x32_bf16 v[22:25], v[164:167], v[196:199], v[22:25]
	v_mfma_f32_16x16x32_bf16 v[18:21], v[172:175], v[196:199], v[18:21]
	v_mfma_f32_16x16x32_bf16 v[6:9], v[164:167], v[204:207], v[6:9]
	v_mfma_f32_16x16x32_bf16 v[2:5], v[172:175], v[204:207], v[2:5]
	v_mfma_f32_16x16x32_bf16 v[54:57], v[168:171], v[184:187], v[54:57]
	v_mfma_f32_16x16x32_bf16 v[50:53], v[176:179], v[184:187], v[50:53]
	v_mfma_f32_16x16x32_bf16 v[38:41], v[168:171], v[192:195], v[38:41]
	v_mfma_f32_16x16x32_bf16 v[34:37], v[176:179], v[192:195], v[34:37]
	v_mfma_f32_16x16x32_bf16 v[22:25], v[168:171], v[200:203], v[22:25]
	v_mfma_f32_16x16x32_bf16 v[18:21], v[176:179], v[200:203], v[18:21]
	v_mfma_f32_16x16x32_bf16 v[6:9], v[168:171], v[208:211], v[6:9]
	v_mfma_f32_16x16x32_bf16 v[2:5], v[176:179], v[208:211], v[2:5]
	s_setprio 0
	s_barrier
	s_add_i32 s39, 0, 0x18000
	v_add_u32_e32 v151, s39, v149
	s_add_i32 s52, 0, 0x1c000
	ds_read_b128 v[142:145], v151
	ds_read_b128 v[152:155], v151 offset:1024
	ds_read_b128 v[156:159], v151 offset:2048
	ds_read_b128 v[160:163], v151 offset:3072
	v_add_u32_e32 v151, s52, v149
	ds_read_b128 v[164:167], v151
	ds_read_b128 v[168:171], v151 offset:1024
	ds_read_b128 v[172:175], v151 offset:2048
	ds_read_b128 v[176:179], v151 offset:3072
	s_add_u32 s44, s50, 0x20000
	s_addc_u32 s45, s51, 0
	s_mov_b32 m0, s67
	v_lshl_add_u64 v[218:219], s[44:45], 0, v[130:131]
	ds_read_b128 v[180:183], v150 offset:32768
	ds_read_b128 v[184:187], v150 offset:33792
	ds_read_b128 v[188:191], v150 offset:34816
	ds_read_b128 v[192:195], v150 offset:35840
	ds_read_b128 v[196:199], v150 offset:36864
	ds_read_b128 v[200:203], v150 offset:37888
	ds_read_b128 v[204:207], v150 offset:38912
	ds_read_b128 v[208:211], v150 offset:39936
	global_load_lds_dwordx4 v[218:219], off
	v_lshl_add_u64 v[218:219], s[44:45], 0, v[134:135]
	s_mov_b32 m0, s74
	s_nop 0
	global_load_lds_dwordx4 v[218:219], off
	s_waitcnt vmcnt(8)
	s_waitcnt lgkmcnt(0)
	s_barrier
	s_setprio 1
	s_waitcnt lgkmcnt(0)
	v_mfma_f32_16x16x32_bf16 v[126:129], v[142:145], v[180:183], v[126:129]
	v_mfma_f32_16x16x32_bf16 v[122:125], v[156:159], v[180:183], v[122:125]
	v_mfma_f32_16x16x32_bf16 v[110:113], v[142:145], v[188:191], v[110:113]
	v_mfma_f32_16x16x32_bf16 v[106:109], v[156:159], v[188:191], v[106:109]
	v_mfma_f32_16x16x32_bf16 v[94:97], v[142:145], v[196:199], v[94:97]
	v_mfma_f32_16x16x32_bf16 v[90:93], v[156:159], v[196:199], v[90:93]
	v_mfma_f32_16x16x32_bf16 v[78:81], v[142:145], v[204:207], v[78:81]
	v_mfma_f32_16x16x32_bf16 v[74:77], v[156:159], v[204:207], v[74:77]
	v_mfma_f32_16x16x32_bf16 v[126:129], v[152:155], v[184:187], v[126:129]
	v_mfma_f32_16x16x32_bf16 v[122:125], v[160:163], v[184:187], v[122:125]
	v_mfma_f32_16x16x32_bf16 v[110:113], v[152:155], v[192:195], v[110:113]
	v_mfma_f32_16x16x32_bf16 v[106:109], v[160:163], v[192:195], v[106:109]
	v_mfma_f32_16x16x32_bf16 v[94:97], v[152:155], v[200:203], v[94:97]
	v_mfma_f32_16x16x32_bf16 v[90:93], v[160:163], v[200:203], v[90:93]
	v_mfma_f32_16x16x32_bf16 v[78:81], v[152:155], v[208:211], v[78:81]
	v_mfma_f32_16x16x32_bf16 v[74:77], v[160:163], v[208:211], v[74:77]
	v_mfma_f32_16x16x32_bf16 v[118:121], v[164:167], v[180:183], v[118:121]
	v_mfma_f32_16x16x32_bf16 v[114:117], v[172:175], v[180:183], v[114:117]
	v_mfma_f32_16x16x32_bf16 v[102:105], v[164:167], v[188:191], v[102:105]
	v_mfma_f32_16x16x32_bf16 v[98:101], v[172:175], v[188:191], v[98:101]
	v_mfma_f32_16x16x32_bf16 v[86:89], v[164:167], v[196:199], v[86:89]
	v_mfma_f32_16x16x32_bf16 v[82:85], v[172:175], v[196:199], v[82:85]
	v_mfma_f32_16x16x32_bf16 v[70:73], v[164:167], v[204:207], v[70:73]
	v_mfma_f32_16x16x32_bf16 v[66:69], v[172:175], v[204:207], v[66:69]
	v_mfma_f32_16x16x32_bf16 v[118:121], v[168:171], v[184:187], v[118:121]
	v_mfma_f32_16x16x32_bf16 v[114:117], v[176:179], v[184:187], v[114:117]
	v_mfma_f32_16x16x32_bf16 v[102:105], v[168:171], v[192:195], v[102:105]
	v_mfma_f32_16x16x32_bf16 v[98:101], v[176:179], v[192:195], v[98:101]
	v_mfma_f32_16x16x32_bf16 v[86:89], v[168:171], v[200:203], v[86:89]
	v_mfma_f32_16x16x32_bf16 v[82:85], v[176:179], v[200:203], v[82:85]
	v_mfma_f32_16x16x32_bf16 v[70:73], v[168:171], v[208:211], v[70:73]
	v_mfma_f32_16x16x32_bf16 v[66:69], v[176:179], v[208:211], v[66:69]
	s_setprio 0
	s_barrier
	s_add_i32 s39, s39, s64
	v_lshl_add_u64 v[146:147], v[146:147], 0, s[42:43]
	s_mov_b32 m0, s39
	ds_read_b128 v[180:183], v150 offset:49152
	ds_read_b128 v[184:187], v150 offset:50176
	ds_read_b128 v[188:191], v150 offset:51200
	ds_read_b128 v[192:195], v150 offset:52224
	ds_read_b128 v[196:199], v150 offset:53248
	ds_read_b128 v[200:203], v150 offset:54272
	ds_read_b128 v[204:207], v150 offset:55296
	ds_read_b128 v[208:211], v150 offset:56320
	global_load_lds_dwordx4 v[146:147], off
	s_add_i32 m0, s39, 0x2000
	s_add_u32 s44, s48, 0x20080
	v_lshl_add_u64 v[146:147], v[212:213], 0, s[42:43]
	s_addc_u32 s45, s49, 0
	s_add_i32 s39, s52, s64
	global_load_lds_dwordx4 v[146:147], off
	v_lshl_add_u64 v[146:147], s[44:45], 0, v[132:133]
	s_mov_b32 m0, s39
	s_nop 0
	global_load_lds_dwordx4 v[146:147], off
	v_lshl_add_u64 v[146:147], s[44:45], 0, v[136:137]
	s_add_i32 m0, s39, 0x2000
	s_nop 0
	global_load_lds_dwordx4 v[146:147], off
	v_lshl_add_u64 v[146:147], v[214:215], 0, s[42:43]
	s_mov_b32 m0, s91
	s_nop 0
	global_load_lds_dwordx4 v[146:147], off
	v_lshl_add_u64 v[146:147], v[216:217], 0, s[42:43]
	s_mov_b32 m0, s92
	s_nop 0
	global_load_lds_dwordx4 v[146:147], off
	s_waitcnt vmcnt(8)
	s_waitcnt lgkmcnt(0)
	s_barrier
	s_setprio 1
	s_waitcnt lgkmcnt(0)
	v_mfma_f32_16x16x32_bf16 v[62:65], v[142:145], v[180:183], v[62:65]
	v_mfma_f32_16x16x32_bf16 v[58:61], v[156:159], v[180:183], v[58:61]
	v_mfma_f32_16x16x32_bf16 v[46:49], v[142:145], v[188:191], v[46:49]
	v_mfma_f32_16x16x32_bf16 v[42:45], v[156:159], v[188:191], v[42:45]
	v_mfma_f32_16x16x32_bf16 v[30:33], v[142:145], v[196:199], v[30:33]
	v_mfma_f32_16x16x32_bf16 v[26:29], v[156:159], v[196:199], v[26:29]
	v_mfma_f32_16x16x32_bf16 v[14:17], v[142:145], v[204:207], v[14:17]
	v_mfma_f32_16x16x32_bf16 v[10:13], v[156:159], v[204:207], v[10:13]
	v_mfma_f32_16x16x32_bf16 v[62:65], v[152:155], v[184:187], v[62:65]
	v_mfma_f32_16x16x32_bf16 v[58:61], v[160:163], v[184:187], v[58:61]
	v_mfma_f32_16x16x32_bf16 v[46:49], v[152:155], v[192:195], v[46:49]
	v_mfma_f32_16x16x32_bf16 v[42:45], v[160:163], v[192:195], v[42:45]
	v_mfma_f32_16x16x32_bf16 v[30:33], v[152:155], v[200:203], v[30:33]
	v_mfma_f32_16x16x32_bf16 v[26:29], v[160:163], v[200:203], v[26:29]
	v_mfma_f32_16x16x32_bf16 v[14:17], v[152:155], v[208:211], v[14:17]
	v_mfma_f32_16x16x32_bf16 v[10:13], v[160:163], v[208:211], v[10:13]
	v_mfma_f32_16x16x32_bf16 v[54:57], v[164:167], v[180:183], v[54:57]
	v_mfma_f32_16x16x32_bf16 v[50:53], v[172:175], v[180:183], v[50:53]
	v_mfma_f32_16x16x32_bf16 v[38:41], v[164:167], v[188:191], v[38:41]
	v_mfma_f32_16x16x32_bf16 v[34:37], v[172:175], v[188:191], v[34:37]
	v_mfma_f32_16x16x32_bf16 v[22:25], v[164:167], v[196:199], v[22:25]
	v_mfma_f32_16x16x32_bf16 v[18:21], v[172:175], v[196:199], v[18:21]
	v_mfma_f32_16x16x32_bf16 v[6:9], v[164:167], v[204:207], v[6:9]
	v_mfma_f32_16x16x32_bf16 v[2:5], v[172:175], v[204:207], v[2:5]
	v_mfma_f32_16x16x32_bf16 v[54:57], v[168:171], v[184:187], v[54:57]
	v_mfma_f32_16x16x32_bf16 v[50:53], v[176:179], v[184:187], v[50:53]
	v_mfma_f32_16x16x32_bf16 v[38:41], v[168:171], v[192:195], v[38:41]
	v_mfma_f32_16x16x32_bf16 v[34:37], v[176:179], v[192:195], v[34:37]
	v_mfma_f32_16x16x32_bf16 v[22:25], v[168:171], v[200:203], v[22:25]
	v_mfma_f32_16x16x32_bf16 v[18:21], v[176:179], v[200:203], v[18:21]
	v_mfma_f32_16x16x32_bf16 v[6:9], v[168:171], v[208:211], v[6:9]
	v_mfma_f32_16x16x32_bf16 v[2:5], v[176:179], v[208:211], v[2:5]
	s_setprio 0
	s_barrier
	s_add_i32 s37, s37, 2
	s_add_u32 s35, s35, 0x100
	s_addc_u32 s36, s36, 0
	s_cmp_gt_u32 s37, 5
	s_mov_b64 s[44:45], s[46:47]
	s_cbranch_scc0 .LBB0_292
	s_and_b64 vcc, exec, s[16:17]
	s_cbranch_vccz .LBB0_295
	s_barrier

.LBB0_335:
	s_add_u32 s22, s20, 0x100
	s_addc_u32 s23, s21, 0
	s_add_i32 s58, 0, 0x10000
	s_cmp_eq_u32 s64, 40
	s_cselect_b32 s39, s7, s23
	s_cselect_b32 s38, s6, s22
	v_add_u32_e32 v149, s58, v147
	s_cselect_b32 s27, s19, s61
	s_cselect_b32 s26, s18, s60
	s_add_i32 s65, 0, 0x14000
	ds_read_b128 v[142:145], v149
	ds_read_b128 v[150:153], v149 offset:1024
	ds_read_b128 v[154:157], v149 offset:2048
	ds_read_b128 v[158:161], v149 offset:3072
	v_add_u32_e32 v149, s65, v147
	ds_read_b128 v[162:165], v149
	ds_read_b128 v[166:169], v149 offset:1024
	ds_read_b128 v[170:173], v149 offset:2048
	ds_read_b128 v[174:177], v149 offset:3072
	v_lshl_add_u64 v[210:211], s[20:21], 0, v[138:139]
	s_add_i32 m0, s44, 0xc000
	ds_read_b128 v[178:181], v148
	ds_read_b128 v[182:185], v148 offset:1024
	ds_read_b128 v[186:189], v148 offset:2048
	ds_read_b128 v[190:193], v148 offset:3072
	ds_read_b128 v[194:197], v148 offset:4096
	ds_read_b128 v[198:201], v148 offset:5120
	ds_read_b128 v[202:205], v148 offset:6144
	ds_read_b128 v[206:209], v148 offset:7168
	global_load_lds_dwordx4 v[210:211], off
	v_lshl_add_u64 v[210:211], s[20:21], 0, v[140:141]
	s_add_i32 m0, s44, 0xe000
	s_nop 0
	global_load_lds_dwordx4 v[210:211], off
	s_waitcnt vmcnt(8)
	s_waitcnt lgkmcnt(0)
	s_barrier
	s_setprio 1
	s_waitcnt lgkmcnt(0)
	v_mfma_f32_16x16x32_bf16 v[126:129], v[142:145], v[178:181], v[126:129]
	v_mfma_f32_16x16x32_bf16 v[122:125], v[154:157], v[178:181], v[122:125]
	v_mfma_f32_16x16x32_bf16 v[114:117], v[142:145], v[186:189], v[114:117]
	v_mfma_f32_16x16x32_bf16 v[110:113], v[154:157], v[186:189], v[110:113]
	v_mfma_f32_16x16x32_bf16 v[98:101], v[142:145], v[194:197], v[98:101]
	v_mfma_f32_16x16x32_bf16 v[94:97], v[154:157], v[194:197], v[94:97]
	v_mfma_f32_16x16x32_bf16 v[82:85], v[142:145], v[202:205], v[82:85]
	v_mfma_f32_16x16x32_bf16 v[78:81], v[154:157], v[202:205], v[78:81]
	v_mfma_f32_16x16x32_bf16 v[126:129], v[150:153], v[182:185], v[126:129]
	v_mfma_f32_16x16x32_bf16 v[122:125], v[158:161], v[182:185], v[122:125]
	v_mfma_f32_16x16x32_bf16 v[114:117], v[150:153], v[190:193], v[114:117]
	v_mfma_f32_16x16x32_bf16 v[110:113], v[158:161], v[190:193], v[110:113]
	v_mfma_f32_16x16x32_bf16 v[98:101], v[150:153], v[198:201], v[98:101]
	v_mfma_f32_16x16x32_bf16 v[94:97], v[158:161], v[198:201], v[94:97]
	v_mfma_f32_16x16x32_bf16 v[82:85], v[150:153], v[206:209], v[82:85]
	v_mfma_f32_16x16x32_bf16 v[78:81], v[158:161], v[206:209], v[78:81]
	v_mfma_f32_16x16x32_bf16 v[118:121], v[162:165], v[178:181], v[118:121]
	v_mfma_f32_16x16x32_bf16 v[106:109], v[170:173], v[178:181], v[106:109]
	v_mfma_f32_16x16x32_bf16 v[102:105], v[162:165], v[186:189], v[102:105]
	v_mfma_f32_16x16x32_bf16 v[90:93], v[170:173], v[186:189], v[90:93]
	v_mfma_f32_16x16x32_bf16 v[86:89], v[162:165], v[194:197], v[86:89]
	v_mfma_f32_16x16x32_bf16 v[74:77], v[170:173], v[194:197], v[74:77]
	v_mfma_f32_16x16x32_bf16 v[70:73], v[162:165], v[202:205], v[70:73]
	v_mfma_f32_16x16x32_bf16 v[66:69], v[170:173], v[202:205], v[66:69]
	v_mfma_f32_16x16x32_bf16 v[118:121], v[166:169], v[182:185], v[118:121]
	v_mfma_f32_16x16x32_bf16 v[106:109], v[174:177], v[182:185], v[106:109]
	v_mfma_f32_16x16x32_bf16 v[102:105], v[166:169], v[190:193], v[102:105]
	v_mfma_f32_16x16x32_bf16 v[90:93], v[174:177], v[190:193], v[90:93]
	v_mfma_f32_16x16x32_bf16 v[86:89], v[166:169], v[198:201], v[86:89]
	v_mfma_f32_16x16x32_bf16 v[74:77], v[174:177], v[198:201], v[74:77]
	v_mfma_f32_16x16x32_bf16 v[70:73], v[166:169], v[206:209], v[70:73]
	v_mfma_f32_16x16x32_bf16 v[66:69], v[174:177], v[206:209], v[66:69]
	s_setprio 0
	s_barrier
	s_add_i32 s20, s58, s37
	v_lshl_add_u64 v[210:211], s[26:27], 0, v[132:133]
	s_mov_b32 m0, s20
	ds_read_b128 v[178:181], v148 offset:16384
	ds_read_b128 v[182:185], v148 offset:17408
	ds_read_b128 v[186:189], v148 offset:18432
	ds_read_b128 v[190:193], v148 offset:19456
	ds_read_b128 v[194:197], v148 offset:20480
	ds_read_b128 v[198:201], v148 offset:21504
	ds_read_b128 v[202:205], v148 offset:22528
	ds_read_b128 v[206:209], v148 offset:23552
	global_load_lds_dwordx4 v[210:211], off
	s_add_i32 m0, s20, 0x2000
	s_add_u32 s20, s26, 0xb0000
	v_lshl_add_u64 v[212:213], s[26:27], 0, v[136:137]
	s_addc_u32 s21, s27, 0
	s_add_i32 s58, s65, s37
	global_load_lds_dwordx4 v[212:213], off
	v_lshl_add_u64 v[214:215], s[20:21], 0, v[132:133]
	s_mov_b32 m0, s58
	v_lshl_add_u64 v[216:217], s[38:39], 0, v[134:135]
	global_load_lds_dwordx4 v[214:215], off
	v_lshl_add_u64 v[214:215], s[20:21], 0, v[136:137]
	s_add_i32 m0, s58, 0x2000
	s_nop 0
	global_load_lds_dwordx4 v[214:215], off
	v_lshl_add_u64 v[214:215], s[38:39], 0, v[130:131]
	s_mov_b32 m0, s44
	s_nop 0
	global_load_lds_dwordx4 v[214:215], off
	s_mov_b32 m0, s45
	s_nop 0
	global_load_lds_dwordx4 v[216:217], off
	s_waitcnt vmcnt(8)
	s_waitcnt lgkmcnt(0)
	s_barrier
	s_setprio 1
	s_waitcnt lgkmcnt(0)
	v_mfma_f32_16x16x32_bf16 v[62:65], v[142:145], v[178:181], v[62:65]
	v_mfma_f32_16x16x32_bf16 v[58:61], v[154:157], v[178:181], v[58:61]
	v_mfma_f32_16x16x32_bf16 v[50:53], v[142:145], v[186:189], v[50:53]
	v_mfma_f32_16x16x32_bf16 v[46:49], v[154:157], v[186:189], v[46:49]
	v_mfma_f32_16x16x32_bf16 v[34:37], v[142:145], v[194:197], v[34:37]
	v_mfma_f32_16x16x32_bf16 v[30:33], v[154:157], v[194:197], v[30:33]
	v_mfma_f32_16x16x32_bf16 v[18:21], v[142:145], v[202:205], v[18:21]
	v_mfma_f32_16x16x32_bf16 v[14:17], v[154:157], v[202:205], v[14:17]
	v_mfma_f32_16x16x32_bf16 v[62:65], v[150:153], v[182:185], v[62:65]
	v_mfma_f32_16x16x32_bf16 v[58:61], v[158:161], v[182:185], v[58:61]
	v_mfma_f32_16x16x32_bf16 v[50:53], v[150:153], v[190:193], v[50:53]
	v_mfma_f32_16x16x32_bf16 v[46:49], v[158:161], v[190:193], v[46:49]
	v_mfma_f32_16x16x32_bf16 v[34:37], v[150:153], v[198:201], v[34:37]
	v_mfma_f32_16x16x32_bf16 v[30:33], v[158:161], v[198:201], v[30:33]
	v_mfma_f32_16x16x32_bf16 v[18:21], v[150:153], v[206:209], v[18:21]
	v_mfma_f32_16x16x32_bf16 v[14:17], v[158:161], v[206:209], v[14:17]
	v_mfma_f32_16x16x32_bf16 v[54:57], v[162:165], v[178:181], v[54:57]
	v_mfma_f32_16x16x32_bf16 v[42:45], v[170:173], v[178:181], v[42:45]
	v_mfma_f32_16x16x32_bf16 v[38:41], v[162:165], v[186:189], v[38:41]
	v_mfma_f32_16x16x32_bf16 v[26:29], v[170:173], v[186:189], v[26:29]
	v_mfma_f32_16x16x32_bf16 v[22:25], v[162:165], v[194:197], v[22:25]
	v_mfma_f32_16x16x32_bf16 v[10:13], v[170:173], v[194:197], v[10:13]
	v_mfma_f32_16x16x32_bf16 v[6:9], v[162:165], v[202:205], v[6:9]
	v_mfma_f32_16x16x32_bf16 v[2:5], v[170:173], v[202:205], v[2:5]
	v_mfma_f32_16x16x32_bf16 v[54:57], v[166:169], v[182:185], v[54:57]
	v_mfma_f32_16x16x32_bf16 v[42:45], v[174:177], v[182:185], v[42:45]
	v_mfma_f32_16x16x32_bf16 v[38:41], v[166:169], v[190:193], v[38:41]
	v_mfma_f32_16x16x32_bf16 v[26:29], v[174:177], v[190:193], v[26:29]
	v_mfma_f32_16x16x32_bf16 v[22:25], v[166:169], v[198:201], v[22:25]
	v_mfma_f32_16x16x32_bf16 v[10:13], v[174:177], v[198:201], v[10:13]
	v_mfma_f32_16x16x32_bf16 v[6:9], v[166:169], v[206:209], v[6:9]
	v_mfma_f32_16x16x32_bf16 v[2:5], v[174:177], v[206:209], v[2:5]
	s_setprio 0
	s_barrier
	s_add_i32 s58, 0, 0x18000
	v_add_u32_e32 v149, s58, v147
	s_add_i32 s65, 0, 0x1c000
	ds_read_b128 v[142:145], v149
	ds_read_b128 v[150:153], v149 offset:1024
	ds_read_b128 v[154:157], v149 offset:2048
	ds_read_b128 v[158:161], v149 offset:3072
	v_add_u32_e32 v149, s65, v147
	ds_read_b128 v[162:165], v149
	ds_read_b128 v[166:169], v149 offset:1024
	ds_read_b128 v[170:173], v149 offset:2048
	ds_read_b128 v[174:177], v149 offset:3072
	s_add_u32 s20, s38, 0xb0000
	s_addc_u32 s21, s39, 0
	s_mov_b32 m0, s46
	v_lshl_add_u64 v[218:219], s[20:21], 0, v[130:131]
	ds_read_b128 v[178:181], v148 offset:32768
	ds_read_b128 v[182:185], v148 offset:33792
	ds_read_b128 v[186:189], v148 offset:34816
	ds_read_b128 v[190:193], v148 offset:35840
	ds_read_b128 v[194:197], v148 offset:36864
	ds_read_b128 v[198:201], v148 offset:37888
	ds_read_b128 v[202:205], v148 offset:38912
	ds_read_b128 v[206:209], v148 offset:39936
	global_load_lds_dwordx4 v[218:219], off
	v_lshl_add_u64 v[218:219], s[20:21], 0, v[134:135]
	s_mov_b32 m0, s47
	s_nop 0
	global_load_lds_dwordx4 v[218:219], off
	s_waitcnt vmcnt(8)
	s_waitcnt lgkmcnt(0)
	s_barrier
	s_setprio 1
	s_waitcnt lgkmcnt(0)
	v_mfma_f32_16x16x32_bf16 v[126:129], v[142:145], v[178:181], v[126:129]
	v_mfma_f32_16x16x32_bf16 v[122:125], v[154:157], v[178:181], v[122:125]
	v_mfma_f32_16x16x32_bf16 v[114:117], v[142:145], v[186:189], v[114:117]
	v_mfma_f32_16x16x32_bf16 v[110:113], v[154:157], v[186:189], v[110:113]
	v_mfma_f32_16x16x32_bf16 v[98:101], v[142:145], v[194:197], v[98:101]
	v_mfma_f32_16x16x32_bf16 v[94:97], v[154:157], v[194:197], v[94:97]
	v_mfma_f32_16x16x32_bf16 v[82:85], v[142:145], v[202:205], v[82:85]
	v_mfma_f32_16x16x32_bf16 v[78:81], v[154:157], v[202:205], v[78:81]
	v_mfma_f32_16x16x32_bf16 v[126:129], v[150:153], v[182:185], v[126:129]
	v_mfma_f32_16x16x32_bf16 v[122:125], v[158:161], v[182:185], v[122:125]
	v_mfma_f32_16x16x32_bf16 v[114:117], v[150:153], v[190:193], v[114:117]
	v_mfma_f32_16x16x32_bf16 v[110:113], v[158:161], v[190:193], v[110:113]
	v_mfma_f32_16x16x32_bf16 v[98:101], v[150:153], v[198:201], v[98:101]
	v_mfma_f32_16x16x32_bf16 v[94:97], v[158:161], v[198:201], v[94:97]
	v_mfma_f32_16x16x32_bf16 v[82:85], v[150:153], v[206:209], v[82:85]
	v_mfma_f32_16x16x32_bf16 v[78:81], v[158:161], v[206:209], v[78:81]
	v_mfma_f32_16x16x32_bf16 v[118:121], v[162:165], v[178:181], v[118:121]
	v_mfma_f32_16x16x32_bf16 v[106:109], v[170:173], v[178:181], v[106:109]
	v_mfma_f32_16x16x32_bf16 v[102:105], v[162:165], v[186:189], v[102:105]
	v_mfma_f32_16x16x32_bf16 v[90:93], v[170:173], v[186:189], v[90:93]
	v_mfma_f32_16x16x32_bf16 v[86:89], v[162:165], v[194:197], v[86:89]
	v_mfma_f32_16x16x32_bf16 v[74:77], v[170:173], v[194:197], v[74:77]
	v_mfma_f32_16x16x32_bf16 v[70:73], v[162:165], v[202:205], v[70:73]
	v_mfma_f32_16x16x32_bf16 v[66:69], v[170:173], v[202:205], v[66:69]
	v_mfma_f32_16x16x32_bf16 v[118:121], v[166:169], v[182:185], v[118:121]
	v_mfma_f32_16x16x32_bf16 v[106:109], v[174:177], v[182:185], v[106:109]
	v_mfma_f32_16x16x32_bf16 v[102:105], v[166:169], v[190:193], v[102:105]
	v_mfma_f32_16x16x32_bf16 v[90:93], v[174:177], v[190:193], v[90:93]
	v_mfma_f32_16x16x32_bf16 v[86:89], v[166:169], v[198:201], v[86:89]
	v_mfma_f32_16x16x32_bf16 v[74:77], v[174:177], v[198:201], v[74:77]
	v_mfma_f32_16x16x32_bf16 v[70:73], v[166:169], v[206:209], v[70:73]
	v_mfma_f32_16x16x32_bf16 v[66:69], v[174:177], v[206:209], v[66:69]
	s_setprio 0
	s_barrier
	s_add_i32 s20, s58, s37
	v_lshl_add_u64 v[210:211], v[210:211], 0, s[42:43]
	s_mov_b32 m0, s20
	ds_read_b128 v[178:181], v148 offset:49152
	ds_read_b128 v[182:185], v148 offset:50176
	ds_read_b128 v[186:189], v148 offset:51200
	ds_read_b128 v[190:193], v148 offset:52224
	ds_read_b128 v[194:197], v148 offset:53248
	ds_read_b128 v[198:201], v148 offset:54272
	ds_read_b128 v[202:205], v148 offset:55296
	ds_read_b128 v[206:209], v148 offset:56320
	global_load_lds_dwordx4 v[210:211], off
	s_add_i32 m0, s20, 0x2000
	s_add_u32 s20, s26, 0xb0080
	v_lshl_add_u64 v[210:211], v[212:213], 0, s[42:43]
	s_addc_u32 s21, s27, 0
	s_add_i32 s26, s65, s37
	global_load_lds_dwordx4 v[210:211], off
	v_lshl_add_u64 v[210:211], s[20:21], 0, v[132:133]
	s_mov_b32 m0, s26
	s_nop 0
	global_load_lds_dwordx4 v[210:211], off
	v_lshl_add_u64 v[210:211], s[20:21], 0, v[136:137]
	s_add_i32 m0, s26, 0x2000
	s_nop 0
	global_load_lds_dwordx4 v[210:211], off
	v_lshl_add_u64 v[210:211], v[214:215], 0, s[42:43]
	s_mov_b32 m0, s49
	s_nop 0
	global_load_lds_dwordx4 v[210:211], off
	v_lshl_add_u64 v[210:211], v[216:217], 0, s[42:43]
	s_mov_b32 m0, s50
	s_nop 0
	global_load_lds_dwordx4 v[210:211], off
	s_waitcnt vmcnt(8)
	s_waitcnt lgkmcnt(0)
	s_barrier
	s_setprio 1
	s_waitcnt lgkmcnt(0)
	v_mfma_f32_16x16x32_bf16 v[62:65], v[142:145], v[178:181], v[62:65]
	v_mfma_f32_16x16x32_bf16 v[58:61], v[154:157], v[178:181], v[58:61]
	v_mfma_f32_16x16x32_bf16 v[50:53], v[142:145], v[186:189], v[50:53]
	v_mfma_f32_16x16x32_bf16 v[46:49], v[154:157], v[186:189], v[46:49]
	v_mfma_f32_16x16x32_bf16 v[34:37], v[142:145], v[194:197], v[34:37]
	v_mfma_f32_16x16x32_bf16 v[30:33], v[154:157], v[194:197], v[30:33]
	v_mfma_f32_16x16x32_bf16 v[18:21], v[142:145], v[202:205], v[18:21]
	v_mfma_f32_16x16x32_bf16 v[14:17], v[154:157], v[202:205], v[14:17]
	v_mfma_f32_16x16x32_bf16 v[62:65], v[150:153], v[182:185], v[62:65]
	v_mfma_f32_16x16x32_bf16 v[58:61], v[158:161], v[182:185], v[58:61]
	v_mfma_f32_16x16x32_bf16 v[50:53], v[150:153], v[190:193], v[50:53]
	v_mfma_f32_16x16x32_bf16 v[46:49], v[158:161], v[190:193], v[46:49]
	v_mfma_f32_16x16x32_bf16 v[34:37], v[150:153], v[198:201], v[34:37]
	v_mfma_f32_16x16x32_bf16 v[30:33], v[158:161], v[198:201], v[30:33]
	v_mfma_f32_16x16x32_bf16 v[18:21], v[150:153], v[206:209], v[18:21]
	v_mfma_f32_16x16x32_bf16 v[14:17], v[158:161], v[206:209], v[14:17]
	v_mfma_f32_16x16x32_bf16 v[54:57], v[162:165], v[178:181], v[54:57]
	v_mfma_f32_16x16x32_bf16 v[42:45], v[170:173], v[178:181], v[42:45]
	v_mfma_f32_16x16x32_bf16 v[38:41], v[162:165], v[186:189], v[38:41]
	v_mfma_f32_16x16x32_bf16 v[26:29], v[170:173], v[186:189], v[26:29]
	v_mfma_f32_16x16x32_bf16 v[22:25], v[162:165], v[194:197], v[22:25]
	v_mfma_f32_16x16x32_bf16 v[10:13], v[170:173], v[194:197], v[10:13]
	v_mfma_f32_16x16x32_bf16 v[6:9], v[162:165], v[202:205], v[6:9]
	v_mfma_f32_16x16x32_bf16 v[2:5], v[170:173], v[202:205], v[2:5]
	v_mfma_f32_16x16x32_bf16 v[54:57], v[166:169], v[182:185], v[54:57]
	v_mfma_f32_16x16x32_bf16 v[42:45], v[174:177], v[182:185], v[42:45]
	v_mfma_f32_16x16x32_bf16 v[38:41], v[166:169], v[190:193], v[38:41]
	v_mfma_f32_16x16x32_bf16 v[26:29], v[174:177], v[190:193], v[26:29]
	v_mfma_f32_16x16x32_bf16 v[22:25], v[166:169], v[198:201], v[22:25]
	v_mfma_f32_16x16x32_bf16 v[10:13], v[174:177], v[198:201], v[10:13]
	v_mfma_f32_16x16x32_bf16 v[6:9], v[166:169], v[206:209], v[6:9]
	v_mfma_f32_16x16x32_bf16 v[2:5], v[174:177], v[206:209], v[2:5]
	s_setprio 0
	s_barrier
	s_add_i32 s64, s64, 2
	s_add_u32 s60, s60, 0x100
	s_addc_u32 s61, s61, 0
	s_cmp_gt_u32 s64, 41
	s_mov_b64 s[20:21], s[22:23]
	s_cbranch_scc0 .LBB0_335
	s_and_b64 vcc, exec, s[16:17]
	s_cbranch_vccz .LBB0_338
	s_barrier

.LBB0_409:
	s_add_u32 s34, s46, 0x8080
	s_addc_u32 s35, s47, 0
	s_add_u32 s46, s6, 0x8000
	s_addc_u32 s47, s7, 0
	s_add_i32 s23, 0, 0x10000
	s_add_u32 s36, s8, 0x8000
	s_addc_u32 s37, s9, 0
	s_add_i32 s27, 0, 0x14000
	v_add_u32_e32 v14, s23, v153
	v_add_u32_e32 v30, s27, v153
	ds_read_b128 v[2:5], v14
	ds_read_b128 v[6:9], v14 offset:1024
	ds_read_b128 v[10:13], v14 offset:2048
	ds_read_b128 v[14:17], v14 offset:3072
	ds_read_b128 v[18:21], v30
	ds_read_b128 v[22:25], v30 offset:1024
	ds_read_b128 v[26:29], v30 offset:2048
	ds_read_b128 v[30:33], v30 offset:3072
	v_lshl_add_u64 v[66:67], s[34:35], 0, v[136:137]
	s_add_i32 m0, s64, 0xc000
	ds_read_b128 v[34:37], v154
	ds_read_b128 v[38:41], v154 offset:1024
	ds_read_b128 v[42:45], v154 offset:2048
	ds_read_b128 v[46:49], v154 offset:3072
	ds_read_b128 v[50:53], v154 offset:4096
	ds_read_b128 v[54:57], v154 offset:5120
	ds_read_b128 v[58:61], v154 offset:6144
	ds_read_b128 v[62:65], v154 offset:7168
	global_load_lds_dwordx4 v[66:67], off
	v_lshl_add_u64 v[66:67], s[34:35], 0, v[132:133]
	s_add_i32 m0, s64, 0xe000
	s_nop 0
	global_load_lds_dwordx4 v[66:67], off
	s_waitcnt vmcnt(8)
	s_waitcnt lgkmcnt(0)
	s_barrier
	s_setprio 1
	s_waitcnt lgkmcnt(0)
	v_mfma_f32_16x16x32_bf16 v[90:93], v[2:5], v[58:61], 0
	v_mfma_f32_16x16x32_bf16 v[66:69], v[2:5], v[34:37], 0
	v_mfma_f32_16x16x32_bf16 v[70:73], v[10:13], v[34:37], 0
	v_mfma_f32_16x16x32_bf16 v[74:77], v[2:5], v[42:45], 0
	v_mfma_f32_16x16x32_bf16 v[78:81], v[10:13], v[42:45], 0
	v_mfma_f32_16x16x32_bf16 v[82:85], v[2:5], v[50:53], 0
	v_mfma_f32_16x16x32_bf16 v[86:89], v[10:13], v[50:53], 0
	v_mfma_f32_16x16x32_bf16 v[98:101], v[6:9], v[62:65], v[90:93]
	v_mfma_f32_16x16x32_bf16 v[90:93], v[10:13], v[58:61], 0
	v_mfma_f32_16x16x32_bf16 v[66:69], v[6:9], v[38:41], v[66:69]
	v_mfma_f32_16x16x32_bf16 v[70:73], v[14:17], v[38:41], v[70:73]
	v_mfma_f32_16x16x32_bf16 v[74:77], v[6:9], v[46:49], v[74:77]
	v_mfma_f32_16x16x32_bf16 v[78:81], v[14:17], v[46:49], v[78:81]
	v_mfma_f32_16x16x32_bf16 v[82:85], v[6:9], v[54:57], v[82:85]
	v_mfma_f32_16x16x32_bf16 v[86:89], v[14:17], v[54:57], v[86:89]
	v_mfma_f32_16x16x32_bf16 v[102:105], v[14:17], v[62:65], v[90:93]
	v_mfma_f32_16x16x32_bf16 v[90:93], v[18:21], v[34:37], 0
	v_mfma_f32_16x16x32_bf16 v[34:37], v[26:29], v[34:37], 0
	v_mfma_f32_16x16x32_bf16 v[114:117], v[22:25], v[38:41], v[90:93]
	v_mfma_f32_16x16x32_bf16 v[34:37], v[30:33], v[38:41], v[34:37]
	v_mfma_f32_16x16x32_bf16 v[38:41], v[18:21], v[42:45], 0
	v_mfma_f32_16x16x32_bf16 v[42:45], v[26:29], v[42:45], 0
	v_mfma_f32_16x16x32_bf16 v[38:41], v[22:25], v[46:49], v[38:41]
	v_mfma_f32_16x16x32_bf16 v[42:45], v[30:33], v[46:49], v[42:45]
	v_mfma_f32_16x16x32_bf16 v[46:49], v[18:21], v[50:53], 0
	v_mfma_f32_16x16x32_bf16 v[50:53], v[26:29], v[50:53], 0
	v_mfma_f32_16x16x32_bf16 v[46:49], v[22:25], v[54:57], v[46:49]
	v_mfma_f32_16x16x32_bf16 v[50:53], v[30:33], v[54:57], v[50:53]
	v_mfma_f32_16x16x32_bf16 v[54:57], v[18:21], v[58:61], 0
	v_mfma_f32_16x16x32_bf16 v[58:61], v[26:29], v[58:61], 0
	v_mfma_f32_16x16x32_bf16 v[54:57], v[22:25], v[62:65], v[54:57]
	v_mfma_f32_16x16x32_bf16 v[58:61], v[30:33], v[62:65], v[58:61]
	s_setprio 0
	s_barrier
	s_add_i32 s23, s23, s51
	v_lshl_add_u64 v[150:151], s[8:9], 0, v[134:135]
	s_mov_b32 m0, s23
	ds_read_b128 v[62:65], v154 offset:16384
	ds_read_b128 v[90:93], v154 offset:17408
	ds_read_b128 v[94:97], v154 offset:18432
	ds_read_b128 v[106:109], v154 offset:19456
	ds_read_b128 v[110:113], v154 offset:20480
	ds_read_b128 v[118:121], v154 offset:21504
	ds_read_b128 v[122:125], v154 offset:22528
	ds_read_b128 v[126:129], v154 offset:23552
	global_load_lds_dwordx4 v[150:151], off
	v_lshl_add_u64 v[252:253], s[8:9], 0, v[130:131]
	s_add_i32 m0, s23, 0x2000
	s_add_i32 s23, s27, s51
	global_load_lds_dwordx4 v[252:253], off
	v_lshl_add_u64 v[138:139], s[36:37], 0, v[134:135]
	s_mov_b32 m0, s23
	v_lshl_add_u64 v[212:213], s[6:7], 0, v[136:137]
	global_load_lds_dwordx4 v[138:139], off
	v_lshl_add_u64 v[138:139], s[36:37], 0, v[130:131]
	s_add_i32 m0, s23, 0x2000
	v_lshl_add_u64 v[232:233], s[6:7], 0, v[132:133]
	global_load_lds_dwordx4 v[138:139], off
	s_mov_b32 m0, s64
	s_nop 0
	global_load_lds_dwordx4 v[212:213], off
	s_mov_b32 m0, s65
	s_nop 0
	global_load_lds_dwordx4 v[232:233], off
	s_waitcnt vmcnt(8)
	s_waitcnt lgkmcnt(0)
	s_barrier
	s_setprio 1
	s_waitcnt lgkmcnt(0)
	v_mfma_f32_16x16x32_bf16 v[138:141], v[2:5], v[62:65], 0
	v_mfma_f32_16x16x32_bf16 v[146:149], v[2:5], v[94:97], 0
	v_mfma_f32_16x16x32_bf16 v[160:163], v[2:5], v[110:113], 0
	v_mfma_f32_16x16x32_bf16 v[2:5], v[2:5], v[122:125], 0
	v_mfma_f32_16x16x32_bf16 v[138:141], v[6:9], v[90:93], v[138:141]
	v_mfma_f32_16x16x32_bf16 v[146:149], v[6:9], v[106:109], v[146:149]
	v_mfma_f32_16x16x32_bf16 v[160:163], v[6:9], v[118:121], v[160:163]
	v_mfma_f32_16x16x32_bf16 v[2:5], v[6:9], v[126:129], v[2:5]
	v_mfma_f32_16x16x32_bf16 v[6:9], v[10:13], v[122:125], 0
	v_mfma_f32_16x16x32_bf16 v[142:145], v[10:13], v[62:65], 0
	v_mfma_f32_16x16x32_bf16 v[156:159], v[10:13], v[94:97], 0
	v_mfma_f32_16x16x32_bf16 v[164:167], v[10:13], v[110:113], 0
	v_mfma_f32_16x16x32_bf16 v[6:9], v[14:17], v[126:129], v[6:9]
	v_mfma_f32_16x16x32_bf16 v[142:145], v[14:17], v[90:93], v[142:145]
	v_mfma_f32_16x16x32_bf16 v[156:159], v[14:17], v[106:109], v[156:159]
	v_mfma_f32_16x16x32_bf16 v[164:167], v[14:17], v[118:121], v[164:167]
	v_mfma_f32_16x16x32_bf16 v[10:13], v[18:21], v[62:65], 0
	v_mfma_f32_16x16x32_bf16 v[168:171], v[22:25], v[90:93], v[10:13]
	v_mfma_f32_16x16x32_bf16 v[10:13], v[26:29], v[62:65], 0
	v_mfma_f32_16x16x32_bf16 v[172:175], v[30:33], v[90:93], v[10:13]
	v_mfma_f32_16x16x32_bf16 v[10:13], v[18:21], v[94:97], 0
	v_mfma_f32_16x16x32_bf16 v[176:179], v[22:25], v[106:109], v[10:13]
	v_mfma_f32_16x16x32_bf16 v[10:13], v[26:29], v[94:97], 0
	v_mfma_f32_16x16x32_bf16 v[180:183], v[30:33], v[106:109], v[10:13]
	v_mfma_f32_16x16x32_bf16 v[10:13], v[18:21], v[110:113], 0
	v_mfma_f32_16x16x32_bf16 v[184:187], v[22:25], v[118:121], v[10:13]
	v_mfma_f32_16x16x32_bf16 v[10:13], v[26:29], v[110:113], 0
	v_mfma_f32_16x16x32_bf16 v[188:191], v[30:33], v[118:121], v[10:13]
	v_mfma_f32_16x16x32_bf16 v[10:13], v[18:21], v[122:125], 0
	v_mfma_f32_16x16x32_bf16 v[192:195], v[22:25], v[126:129], v[10:13]
	v_mfma_f32_16x16x32_bf16 v[10:13], v[26:29], v[122:125], 0
	v_mfma_f32_16x16x32_bf16 v[196:199], v[30:33], v[126:129], v[10:13]
	s_setprio 0
	s_barrier
	s_add_i32 s23, 0, 0x18000
	s_add_i32 s27, 0, 0x1c000
	v_add_u32_e32 v22, s23, v153
	v_add_u32_e32 v26, s27, v153
	s_nop 0
	ds_read_b128 v[10:13], v22
	ds_read_b128 v[14:17], v22 offset:1024
	ds_read_b128 v[18:21], v22 offset:2048
	ds_read_b128 v[22:25], v22 offset:3072
	ds_read_b128 v[200:203], v26
	ds_read_b128 v[240:243], v26 offset:1024
	ds_read_b128 v[244:247], v26 offset:2048
	ds_read_b128 v[248:251], v26 offset:3072
	s_mov_b32 m0, s66
	v_lshl_add_u64 v[90:91], s[46:47], 0, v[136:137]
	ds_read_b128 v[26:29], v154 offset:32768
	ds_read_b128 v[30:33], v154 offset:33792
	ds_read_b128 v[62:65], v154 offset:34816
	ds_read_b128 v[218:221], v154 offset:35840
	ds_read_b128 v[214:217], v154 offset:36864
	ds_read_b128 v[208:211], v154 offset:37888
	ds_read_b128 v[204:207], v154 offset:38912
	ds_read_b128 v[222:225], v154 offset:39936
	global_load_lds_dwordx4 v[90:91], off
	v_lshl_add_u64 v[90:91], s[46:47], 0, v[132:133]
	s_mov_b32 m0, s67
	s_nop 0
	global_load_lds_dwordx4 v[90:91], off
	s_waitcnt vmcnt(8)
	s_waitcnt lgkmcnt(0)
	s_barrier
	s_setprio 1
	s_waitcnt lgkmcnt(0)
	v_mfma_f32_16x16x32_bf16 v[66:69], v[10:13], v[26:29], v[66:69]
	v_mfma_f32_16x16x32_bf16 v[122:125], v[14:17], v[30:33], v[66:69]
	v_mfma_f32_16x16x32_bf16 v[66:69], v[18:21], v[26:29], v[70:73]
	v_mfma_f32_16x16x32_bf16 v[126:129], v[22:25], v[30:33], v[66:69]
	v_mfma_f32_16x16x32_bf16 v[66:69], v[10:13], v[62:65], v[74:77]
	v_mfma_f32_16x16x32_bf16 v[106:109], v[14:17], v[218:221], v[66:69]
	v_mfma_f32_16x16x32_bf16 v[66:69], v[18:21], v[62:65], v[78:81]
	v_mfma_f32_16x16x32_bf16 v[110:113], v[22:25], v[218:221], v[66:69]
	v_mfma_f32_16x16x32_bf16 v[66:69], v[10:13], v[214:217], v[82:85]
	v_mfma_f32_16x16x32_bf16 v[90:93], v[14:17], v[208:211], v[66:69]
	v_mfma_f32_16x16x32_bf16 v[66:69], v[18:21], v[214:217], v[86:89]
	v_mfma_f32_16x16x32_bf16 v[94:97], v[22:25], v[208:211], v[66:69]
	v_mfma_f32_16x16x32_bf16 v[66:69], v[10:13], v[204:207], v[98:101]
	v_mfma_f32_16x16x32_bf16 v[74:77], v[14:17], v[222:225], v[66:69]
	v_mfma_f32_16x16x32_bf16 v[66:69], v[18:21], v[204:207], v[102:105]
	v_mfma_f32_16x16x32_bf16 v[78:81], v[22:25], v[222:225], v[66:69]
	v_mfma_f32_16x16x32_bf16 v[66:69], v[200:203], v[26:29], v[114:117]
	v_mfma_f32_16x16x32_bf16 v[26:29], v[244:247], v[26:29], v[34:37]
	v_mfma_f32_16x16x32_bf16 v[118:121], v[248:251], v[30:33], v[26:29]
	v_mfma_f32_16x16x32_bf16 v[26:29], v[200:203], v[62:65], v[38:41]
	v_mfma_f32_16x16x32_bf16 v[98:101], v[240:243], v[218:221], v[26:29]
	v_mfma_f32_16x16x32_bf16 v[26:29], v[244:247], v[62:65], v[42:45]
	v_mfma_f32_16x16x32_bf16 v[102:105], v[248:251], v[218:221], v[26:29]
	v_mfma_f32_16x16x32_bf16 v[26:29], v[200:203], v[214:217], v[46:49]
	v_mfma_f32_16x16x32_bf16 v[82:85], v[240:243], v[208:211], v[26:29]
	v_mfma_f32_16x16x32_bf16 v[26:29], v[244:247], v[214:217], v[50:53]
	v_mfma_f32_16x16x32_bf16 v[86:89], v[248:251], v[208:211], v[26:29]
	v_mfma_f32_16x16x32_bf16 v[26:29], v[200:203], v[204:207], v[54:57]
	v_mfma_f32_16x16x32_bf16 v[114:117], v[240:243], v[30:33], v[66:69]
	v_mfma_f32_16x16x32_bf16 v[66:69], v[240:243], v[222:225], v[26:29]
	v_mfma_f32_16x16x32_bf16 v[26:29], v[244:247], v[204:207], v[58:61]
	v_mfma_f32_16x16x32_bf16 v[70:73], v[248:251], v[222:225], v[26:29]
	s_setprio 0
	s_barrier
	s_add_i32 s23, s23, s51
	s_nop 3
	v_lshl_add_u64 v[26:27], v[150:151], 0, s[42:43]
	s_mov_b32 m0, s23
	ds_read_b128 v[34:37], v154 offset:49152
	ds_read_b128 v[38:41], v154 offset:50176
	ds_read_b128 v[204:207], v154 offset:51200
	ds_read_b128 v[208:211], v154 offset:52224
	ds_read_b128 v[214:217], v154 offset:53248
	ds_read_b128 v[218:221], v154 offset:54272
	ds_read_b128 v[222:225], v154 offset:55296
	ds_read_b128 v[226:229], v154 offset:56320
	global_load_lds_dwordx4 v[26:27], off
	s_add_i32 m0, s23, 0x2000
	s_add_u32 s34, s8, 0x8080
	v_lshl_add_u64 v[26:27], v[252:253], 0, s[42:43]
	s_addc_u32 s35, s9, 0
	s_add_i32 s23, s27, s51
	global_load_lds_dwordx4 v[26:27], off
	v_lshl_add_u64 v[26:27], s[34:35], 0, v[134:135]
	s_mov_b32 m0, s23
	s_nop 0
	global_load_lds_dwordx4 v[26:27], off
	v_lshl_add_u64 v[26:27], s[34:35], 0, v[130:131]
	s_add_i32 m0, s23, 0x2000
	s_nop 0
	global_load_lds_dwordx4 v[26:27], off
	v_lshl_add_u64 v[26:27], v[212:213], 0, s[42:43]
	s_mov_b32 m0, s92
	s_nop 0
	global_load_lds_dwordx4 v[26:27], off
	v_lshl_add_u64 v[26:27], v[232:233], 0, s[42:43]
	s_mov_b32 m0, s93
	s_nop 0
	global_load_lds_dwordx4 v[26:27], off
	s_waitcnt vmcnt(8)
	s_waitcnt lgkmcnt(0)
	s_barrier
	s_setprio 1
	s_waitcnt lgkmcnt(0)
	v_mfma_f32_16x16x32_bf16 v[26:29], v[10:13], v[34:37], v[138:141]
	v_mfma_f32_16x16x32_bf16 v[58:61], v[14:17], v[38:41], v[26:29]
	v_mfma_f32_16x16x32_bf16 v[26:29], v[18:21], v[34:37], v[142:145]
	v_mfma_f32_16x16x32_bf16 v[62:65], v[22:25], v[38:41], v[26:29]
	v_mfma_f32_16x16x32_bf16 v[26:29], v[10:13], v[204:207], v[146:149]
	v_mfma_f32_16x16x32_bf16 v[42:45], v[14:17], v[208:211], v[26:29]
	v_mfma_f32_16x16x32_bf16 v[26:29], v[18:21], v[204:207], v[156:159]
	v_mfma_f32_16x16x32_bf16 v[2:5], v[10:13], v[222:225], v[2:5]
	v_mfma_f32_16x16x32_bf16 v[46:49], v[22:25], v[208:211], v[26:29]
	v_mfma_f32_16x16x32_bf16 v[26:29], v[10:13], v[214:217], v[160:163]
	v_mfma_f32_16x16x32_bf16 v[30:33], v[18:21], v[214:217], v[164:167]
	v_mfma_f32_16x16x32_bf16 v[10:13], v[14:17], v[226:229], v[2:5]
	v_mfma_f32_16x16x32_bf16 v[2:5], v[18:21], v[222:225], v[6:9]
	v_mfma_f32_16x16x32_bf16 v[26:29], v[14:17], v[218:221], v[26:29]
	v_mfma_f32_16x16x32_bf16 v[30:33], v[22:25], v[218:221], v[30:33]
	v_mfma_f32_16x16x32_bf16 v[14:17], v[22:25], v[226:229], v[2:5]
	v_mfma_f32_16x16x32_bf16 v[2:5], v[200:203], v[34:37], v[168:171]
	v_mfma_f32_16x16x32_bf16 v[50:53], v[240:243], v[38:41], v[2:5]
	v_mfma_f32_16x16x32_bf16 v[2:5], v[244:247], v[34:37], v[172:175]
	v_mfma_f32_16x16x32_bf16 v[54:57], v[248:251], v[38:41], v[2:5]
	v_mfma_f32_16x16x32_bf16 v[2:5], v[200:203], v[204:207], v[176:179]
	v_mfma_f32_16x16x32_bf16 v[34:37], v[240:243], v[208:211], v[2:5]
	v_mfma_f32_16x16x32_bf16 v[2:5], v[244:247], v[204:207], v[180:183]
	v_mfma_f32_16x16x32_bf16 v[38:41], v[248:251], v[208:211], v[2:5]
	v_mfma_f32_16x16x32_bf16 v[2:5], v[200:203], v[214:217], v[184:187]
	v_mfma_f32_16x16x32_bf16 v[18:21], v[240:243], v[218:221], v[2:5]
	v_mfma_f32_16x16x32_bf16 v[2:5], v[244:247], v[214:217], v[188:191]
	v_mfma_f32_16x16x32_bf16 v[22:25], v[248:251], v[218:221], v[2:5]
	v_mfma_f32_16x16x32_bf16 v[2:5], v[200:203], v[222:225], v[192:195]
	v_mfma_f32_16x16x32_bf16 v[6:9], v[244:247], v[222:225], v[196:199]
	v_mfma_f32_16x16x32_bf16 v[2:5], v[240:243], v[226:229], v[2:5]
	v_mfma_f32_16x16x32_bf16 v[6:9], v[248:251], v[226:229], v[6:9]
	s_setprio 0
	s_barrier
	s_andn2_b64 vcc, exec, s[18:19]
	s_cbranch_vccnz .LBB0_411
	s_barrier

.LBB0_563:
	s_add_u32 s46, s44, 0x100
	s_addc_u32 s47, s45, 0
	s_add_i32 s75, 0, 0x10000
	s_cmp_eq_u32 s21, 4
	s_cselect_b32 s51, s9, s47
	s_cselect_b32 s50, s8, s46
	s_cselect_b32 s49, s23, s19
	s_cselect_b32 s48, s22, s17
	s_add_i32 s77, 0, 0x14000
	v_add_u32_e32 v154, s75, v162
	v_add_u32_e32 v176, s77, v162
	ds_read_b128 v[142:145], v154
	ds_read_b128 v[146:149], v154 offset:1024
	ds_read_b128 v[150:153], v154 offset:2048
	ds_read_b128 v[154:157], v154 offset:3072
	ds_read_b128 v[164:167], v176
	ds_read_b128 v[168:171], v176 offset:1024
	ds_read_b128 v[172:175], v176 offset:2048
	ds_read_b128 v[176:179], v176 offset:3072
	v_lshl_add_u64 v[204:205], s[44:45], 0, v[138:139]
	s_add_i32 m0, s37, 0xc000
	ds_read_b128 v[180:183], v163
	ds_read_b128 v[184:187], v163 offset:1024
	ds_read_b128 v[188:191], v163 offset:2048
	ds_read_b128 v[192:195], v163 offset:3072
	ds_read_b128 v[196:199], v163 offset:4096
	ds_read_b128 v[200:203], v163 offset:5120
	ds_read_b128 v[240:243], v163 offset:6144
	ds_read_b128 v[244:247], v163 offset:7168
	global_load_lds_dwordx4 v[204:205], off
	v_lshl_add_u64 v[204:205], s[44:45], 0, v[140:141]
	s_add_i32 m0, s37, 0xe000
	s_nop 0
	global_load_lds_dwordx4 v[204:205], off
	s_waitcnt vmcnt(8)
	s_waitcnt lgkmcnt(0)
	s_barrier
	s_setprio 1
	s_waitcnt lgkmcnt(0)
	v_mfma_f32_16x16x32_bf16 v[126:129], v[142:145], v[180:183], v[126:129]
	v_mfma_f32_16x16x32_bf16 v[122:125], v[150:153], v[180:183], v[122:125]
	v_mfma_f32_16x16x32_bf16 v[118:121], v[142:145], v[188:191], v[118:121]
	v_mfma_f32_16x16x32_bf16 v[110:113], v[150:153], v[188:191], v[110:113]
	v_mfma_f32_16x16x32_bf16 v[102:105], v[142:145], v[196:199], v[102:105]
	v_mfma_f32_16x16x32_bf16 v[98:101], v[150:153], v[196:199], v[98:101]
	v_mfma_f32_16x16x32_bf16 v[86:89], v[142:145], v[240:243], v[86:89]
	v_mfma_f32_16x16x32_bf16 v[82:85], v[150:153], v[240:243], v[82:85]
	v_mfma_f32_16x16x32_bf16 v[126:129], v[146:149], v[184:187], v[126:129]
	v_mfma_f32_16x16x32_bf16 v[122:125], v[154:157], v[184:187], v[122:125]
	v_mfma_f32_16x16x32_bf16 v[118:121], v[146:149], v[192:195], v[118:121]
	v_mfma_f32_16x16x32_bf16 v[110:113], v[154:157], v[192:195], v[110:113]
	v_mfma_f32_16x16x32_bf16 v[102:105], v[146:149], v[200:203], v[102:105]
	v_mfma_f32_16x16x32_bf16 v[98:101], v[154:157], v[200:203], v[98:101]
	v_mfma_f32_16x16x32_bf16 v[86:89], v[146:149], v[244:247], v[86:89]
	v_mfma_f32_16x16x32_bf16 v[82:85], v[154:157], v[244:247], v[82:85]
	v_mfma_f32_16x16x32_bf16 v[114:117], v[164:167], v[180:183], v[114:117]
	v_mfma_f32_16x16x32_bf16 v[106:109], v[172:175], v[180:183], v[106:109]
	v_mfma_f32_16x16x32_bf16 v[94:97], v[164:167], v[188:191], v[94:97]
	v_mfma_f32_16x16x32_bf16 v[90:93], v[172:175], v[188:191], v[90:93]
	v_mfma_f32_16x16x32_bf16 v[78:81], v[164:167], v[196:199], v[78:81]
	v_mfma_f32_16x16x32_bf16 v[74:77], v[172:175], v[196:199], v[74:77]
	v_mfma_f32_16x16x32_bf16 v[70:73], v[164:167], v[240:243], v[70:73]
	v_mfma_f32_16x16x32_bf16 v[66:69], v[172:175], v[240:243], v[66:69]
	v_mfma_f32_16x16x32_bf16 v[114:117], v[168:171], v[184:187], v[114:117]
	v_mfma_f32_16x16x32_bf16 v[106:109], v[176:179], v[184:187], v[106:109]
	v_mfma_f32_16x16x32_bf16 v[94:97], v[168:171], v[192:195], v[94:97]
	v_mfma_f32_16x16x32_bf16 v[90:93], v[176:179], v[192:195], v[90:93]
	v_mfma_f32_16x16x32_bf16 v[78:81], v[168:171], v[200:203], v[78:81]
	v_mfma_f32_16x16x32_bf16 v[74:77], v[176:179], v[200:203], v[74:77]
	v_mfma_f32_16x16x32_bf16 v[70:73], v[168:171], v[244:247], v[70:73]
	v_mfma_f32_16x16x32_bf16 v[66:69], v[176:179], v[244:247], v[66:69]
	s_setprio 0
	s_barrier
	s_add_i32 s44, s75, s36
	v_lshl_add_u64 v[204:205], s[48:49], 0, v[134:135]
	s_mov_b32 m0, s44
	ds_read_b128 v[180:183], v163 offset:16384
	ds_read_b128 v[184:187], v163 offset:17408
	ds_read_b128 v[188:191], v163 offset:18432
	ds_read_b128 v[192:195], v163 offset:19456
	ds_read_b128 v[196:199], v163 offset:20480
	ds_read_b128 v[200:203], v163 offset:21504
	ds_read_b128 v[240:243], v163 offset:22528
	ds_read_b128 v[244:247], v163 offset:23552
	global_load_lds_dwordx4 v[204:205], off
	s_add_i32 m0, s44, 0x2000
	s_add_u32 s44, s48, 0x20000
	v_lshl_add_u64 v[206:207], s[48:49], 0, v[130:131]
	s_addc_u32 s45, s49, 0
	s_add_i32 s75, s77, s36
	global_load_lds_dwordx4 v[206:207], off
	v_lshl_add_u64 v[208:209], s[44:45], 0, v[134:135]
	s_mov_b32 m0, s75
	v_lshl_add_u64 v[210:211], s[50:51], 0, v[132:133]
	global_load_lds_dwordx4 v[208:209], off
	v_lshl_add_u64 v[208:209], s[44:45], 0, v[130:131]
	s_add_i32 m0, s75, 0x2000
	s_nop 0
	global_load_lds_dwordx4 v[208:209], off
	v_lshl_add_u64 v[208:209], s[50:51], 0, v[136:137]
	s_mov_b32 m0, s37
	s_nop 0
	global_load_lds_dwordx4 v[208:209], off
	s_mov_b32 m0, s52
	s_nop 0
	global_load_lds_dwordx4 v[210:211], off
	s_waitcnt vmcnt(8)
	s_waitcnt lgkmcnt(0)
	s_barrier
	s_setprio 1
	s_waitcnt lgkmcnt(0)
	v_mfma_f32_16x16x32_bf16 v[62:65], v[142:145], v[180:183], v[62:65]
	v_mfma_f32_16x16x32_bf16 v[58:61], v[150:153], v[180:183], v[58:61]
	v_mfma_f32_16x16x32_bf16 v[54:57], v[142:145], v[188:191], v[54:57]
	v_mfma_f32_16x16x32_bf16 v[50:53], v[150:153], v[188:191], v[50:53]
	v_mfma_f32_16x16x32_bf16 v[38:41], v[142:145], v[196:199], v[38:41]
	v_mfma_f32_16x16x32_bf16 v[34:37], v[150:153], v[196:199], v[34:37]
	v_mfma_f32_16x16x32_bf16 v[22:25], v[142:145], v[240:243], v[22:25]
	v_mfma_f32_16x16x32_bf16 v[18:21], v[150:153], v[240:243], v[18:21]
	v_mfma_f32_16x16x32_bf16 v[62:65], v[146:149], v[184:187], v[62:65]
	v_mfma_f32_16x16x32_bf16 v[58:61], v[154:157], v[184:187], v[58:61]
	v_mfma_f32_16x16x32_bf16 v[54:57], v[146:149], v[192:195], v[54:57]
	v_mfma_f32_16x16x32_bf16 v[50:53], v[154:157], v[192:195], v[50:53]
	v_mfma_f32_16x16x32_bf16 v[38:41], v[146:149], v[200:203], v[38:41]
	v_mfma_f32_16x16x32_bf16 v[34:37], v[154:157], v[200:203], v[34:37]
	v_mfma_f32_16x16x32_bf16 v[22:25], v[146:149], v[244:247], v[22:25]
	v_mfma_f32_16x16x32_bf16 v[18:21], v[154:157], v[244:247], v[18:21]
	v_mfma_f32_16x16x32_bf16 v[46:49], v[164:167], v[180:183], v[46:49]
	v_mfma_f32_16x16x32_bf16 v[42:45], v[172:175], v[180:183], v[42:45]
	v_mfma_f32_16x16x32_bf16 v[30:33], v[164:167], v[188:191], v[30:33]
	v_mfma_f32_16x16x32_bf16 v[26:29], v[172:175], v[188:191], v[26:29]
	v_mfma_f32_16x16x32_bf16 v[14:17], v[164:167], v[196:199], v[14:17]
	v_mfma_f32_16x16x32_bf16 v[10:13], v[172:175], v[196:199], v[10:13]
	v_mfma_f32_16x16x32_bf16 v[6:9], v[164:167], v[240:243], v[6:9]
	v_mfma_f32_16x16x32_bf16 v[2:5], v[172:175], v[240:243], v[2:5]
	v_mfma_f32_16x16x32_bf16 v[46:49], v[168:171], v[184:187], v[46:49]
	v_mfma_f32_16x16x32_bf16 v[42:45], v[176:179], v[184:187], v[42:45]
	v_mfma_f32_16x16x32_bf16 v[30:33], v[168:171], v[192:195], v[30:33]
	v_mfma_f32_16x16x32_bf16 v[26:29], v[176:179], v[192:195], v[26:29]
	v_mfma_f32_16x16x32_bf16 v[14:17], v[168:171], v[200:203], v[14:17]
	v_mfma_f32_16x16x32_bf16 v[10:13], v[176:179], v[200:203], v[10:13]
	v_mfma_f32_16x16x32_bf16 v[6:9], v[168:171], v[244:247], v[6:9]
	v_mfma_f32_16x16x32_bf16 v[2:5], v[176:179], v[244:247], v[2:5]
	s_setprio 0
	s_barrier
	s_add_i32 s75, 0, 0x18000
	s_add_i32 s77, 0, 0x1c000
	v_add_u32_e32 v154, s75, v162
	v_add_u32_e32 v176, s77, v162
	ds_read_b128 v[142:145], v154
	ds_read_b128 v[146:149], v154 offset:1024
	ds_read_b128 v[150:153], v154 offset:2048
	ds_read_b128 v[154:157], v154 offset:3072
	ds_read_b128 v[164:167], v176
	ds_read_b128 v[168:171], v176 offset:1024
	ds_read_b128 v[172:175], v176 offset:2048
	ds_read_b128 v[176:179], v176 offset:3072
	s_add_u32 s44, s50, 0x20000
	s_addc_u32 s45, s51, 0
	s_mov_b32 m0, s53
	v_lshl_add_u64 v[214:215], s[44:45], 0, v[136:137]
	ds_read_b128 v[180:183], v163 offset:32768
	ds_read_b128 v[184:187], v163 offset:33792
	ds_read_b128 v[188:191], v163 offset:34816
	ds_read_b128 v[192:195], v163 offset:35840
	ds_read_b128 v[196:199], v163 offset:36864
	ds_read_b128 v[200:203], v163 offset:37888
	ds_read_b128 v[240:243], v163 offset:38912
	ds_read_b128 v[244:247], v163 offset:39936
	global_load_lds_dwordx4 v[214:215], off
	v_lshl_add_u64 v[214:215], s[44:45], 0, v[132:133]
	s_mov_b32 m0, s54
	s_nop 0
	global_load_lds_dwordx4 v[214:215], off
	s_waitcnt vmcnt(8)
	s_waitcnt lgkmcnt(0)
	s_barrier
	s_setprio 1
	s_waitcnt lgkmcnt(0)
	v_mfma_f32_16x16x32_bf16 v[126:129], v[142:145], v[180:183], v[126:129]
	v_mfma_f32_16x16x32_bf16 v[122:125], v[150:153], v[180:183], v[122:125]
	v_mfma_f32_16x16x32_bf16 v[118:121], v[142:145], v[188:191], v[118:121]
	v_mfma_f32_16x16x32_bf16 v[110:113], v[150:153], v[188:191], v[110:113]
	v_mfma_f32_16x16x32_bf16 v[102:105], v[142:145], v[196:199], v[102:105]
	v_mfma_f32_16x16x32_bf16 v[98:101], v[150:153], v[196:199], v[98:101]
	v_mfma_f32_16x16x32_bf16 v[86:89], v[142:145], v[240:243], v[86:89]
	v_mfma_f32_16x16x32_bf16 v[82:85], v[150:153], v[240:243], v[82:85]
	v_mfma_f32_16x16x32_bf16 v[126:129], v[146:149], v[184:187], v[126:129]
	v_mfma_f32_16x16x32_bf16 v[122:125], v[154:157], v[184:187], v[122:125]
	v_mfma_f32_16x16x32_bf16 v[118:121], v[146:149], v[192:195], v[118:121]
	v_mfma_f32_16x16x32_bf16 v[110:113], v[154:157], v[192:195], v[110:113]
	v_mfma_f32_16x16x32_bf16 v[102:105], v[146:149], v[200:203], v[102:105]
	v_mfma_f32_16x16x32_bf16 v[98:101], v[154:157], v[200:203], v[98:101]
	v_mfma_f32_16x16x32_bf16 v[86:89], v[146:149], v[244:247], v[86:89]
	v_mfma_f32_16x16x32_bf16 v[82:85], v[154:157], v[244:247], v[82:85]
	v_mfma_f32_16x16x32_bf16 v[114:117], v[164:167], v[180:183], v[114:117]
	v_mfma_f32_16x16x32_bf16 v[106:109], v[172:175], v[180:183], v[106:109]
	v_mfma_f32_16x16x32_bf16 v[94:97], v[164:167], v[188:191], v[94:97]
	v_mfma_f32_16x16x32_bf16 v[90:93], v[172:175], v[188:191], v[90:93]
	v_mfma_f32_16x16x32_bf16 v[78:81], v[164:167], v[196:199], v[78:81]
	v_mfma_f32_16x16x32_bf16 v[74:77], v[172:175], v[196:199], v[74:77]
	v_mfma_f32_16x16x32_bf16 v[70:73], v[164:167], v[240:243], v[70:73]
	v_mfma_f32_16x16x32_bf16 v[66:69], v[172:175], v[240:243], v[66:69]
	v_mfma_f32_16x16x32_bf16 v[114:117], v[168:171], v[184:187], v[114:117]
	v_mfma_f32_16x16x32_bf16 v[106:109], v[176:179], v[184:187], v[106:109]
	v_mfma_f32_16x16x32_bf16 v[94:97], v[168:171], v[192:195], v[94:97]
	v_mfma_f32_16x16x32_bf16 v[90:93], v[176:179], v[192:195], v[90:93]
	v_mfma_f32_16x16x32_bf16 v[78:81], v[168:171], v[200:203], v[78:81]
	v_mfma_f32_16x16x32_bf16 v[74:77], v[176:179], v[200:203], v[74:77]
	v_mfma_f32_16x16x32_bf16 v[70:73], v[168:171], v[244:247], v[70:73]
	v_mfma_f32_16x16x32_bf16 v[66:69], v[176:179], v[244:247], v[66:69]
	s_setprio 0
	s_barrier
	s_add_i32 s44, s75, s36
	v_lshl_add_u64 v[204:205], v[204:205], 0, s[42:43]
	s_mov_b32 m0, s44
	ds_read_b128 v[180:183], v163 offset:49152
	ds_read_b128 v[184:187], v163 offset:50176
	ds_read_b128 v[188:191], v163 offset:51200
	ds_read_b128 v[192:195], v163 offset:52224
	ds_read_b128 v[196:199], v163 offset:53248
	ds_read_b128 v[200:203], v163 offset:54272
	ds_read_b128 v[240:243], v163 offset:55296
	ds_read_b128 v[244:247], v163 offset:56320
	global_load_lds_dwordx4 v[204:205], off
	s_add_i32 m0, s44, 0x2000
	s_add_u32 s44, s48, 0x20080
	v_lshl_add_u64 v[204:205], v[206:207], 0, s[42:43]
	s_addc_u32 s45, s49, 0
	s_add_i32 s48, s77, s36
	global_load_lds_dwordx4 v[204:205], off
	v_lshl_add_u64 v[204:205], s[44:45], 0, v[134:135]
	s_mov_b32 m0, s48
	s_nop 0
	global_load_lds_dwordx4 v[204:205], off
	v_lshl_add_u64 v[204:205], s[44:45], 0, v[130:131]
	s_add_i32 m0, s48, 0x2000
	s_nop 0
	global_load_lds_dwordx4 v[204:205], off
	v_lshl_add_u64 v[204:205], v[208:209], 0, s[42:43]
	s_mov_b32 m0, s65
	s_nop 0
	global_load_lds_dwordx4 v[204:205], off
	v_lshl_add_u64 v[204:205], v[210:211], 0, s[42:43]
	s_mov_b32 m0, s66
	s_nop 0
	global_load_lds_dwordx4 v[204:205], off
	s_waitcnt vmcnt(8)
	s_waitcnt lgkmcnt(0)
	s_barrier
	s_setprio 1
	s_waitcnt lgkmcnt(0)
	v_mfma_f32_16x16x32_bf16 v[62:65], v[142:145], v[180:183], v[62:65]
	v_mfma_f32_16x16x32_bf16 v[58:61], v[150:153], v[180:183], v[58:61]
	v_mfma_f32_16x16x32_bf16 v[54:57], v[142:145], v[188:191], v[54:57]
	v_mfma_f32_16x16x32_bf16 v[50:53], v[150:153], v[188:191], v[50:53]
	v_mfma_f32_16x16x32_bf16 v[38:41], v[142:145], v[196:199], v[38:41]
	v_mfma_f32_16x16x32_bf16 v[34:37], v[150:153], v[196:199], v[34:37]
	v_mfma_f32_16x16x32_bf16 v[22:25], v[142:145], v[240:243], v[22:25]
	v_mfma_f32_16x16x32_bf16 v[18:21], v[150:153], v[240:243], v[18:21]
	v_mfma_f32_16x16x32_bf16 v[62:65], v[146:149], v[184:187], v[62:65]
	v_mfma_f32_16x16x32_bf16 v[58:61], v[154:157], v[184:187], v[58:61]
	v_mfma_f32_16x16x32_bf16 v[54:57], v[146:149], v[192:195], v[54:57]
	v_mfma_f32_16x16x32_bf16 v[50:53], v[154:157], v[192:195], v[50:53]
	v_mfma_f32_16x16x32_bf16 v[38:41], v[146:149], v[200:203], v[38:41]
	v_mfma_f32_16x16x32_bf16 v[34:37], v[154:157], v[200:203], v[34:37]
	v_mfma_f32_16x16x32_bf16 v[22:25], v[146:149], v[244:247], v[22:25]
	v_mfma_f32_16x16x32_bf16 v[18:21], v[154:157], v[244:247], v[18:21]
	v_mfma_f32_16x16x32_bf16 v[46:49], v[164:167], v[180:183], v[46:49]
	v_mfma_f32_16x16x32_bf16 v[42:45], v[172:175], v[180:183], v[42:45]
	v_mfma_f32_16x16x32_bf16 v[30:33], v[164:167], v[188:191], v[30:33]
	v_mfma_f32_16x16x32_bf16 v[26:29], v[172:175], v[188:191], v[26:29]
	v_mfma_f32_16x16x32_bf16 v[14:17], v[164:167], v[196:199], v[14:17]
	v_mfma_f32_16x16x32_bf16 v[10:13], v[172:175], v[196:199], v[10:13]
	v_mfma_f32_16x16x32_bf16 v[6:9], v[164:167], v[240:243], v[6:9]
	v_mfma_f32_16x16x32_bf16 v[2:5], v[172:175], v[240:243], v[2:5]
	v_mfma_f32_16x16x32_bf16 v[46:49], v[168:171], v[184:187], v[46:49]
	v_mfma_f32_16x16x32_bf16 v[42:45], v[176:179], v[184:187], v[42:45]
	v_mfma_f32_16x16x32_bf16 v[30:33], v[168:171], v[192:195], v[30:33]
	v_mfma_f32_16x16x32_bf16 v[26:29], v[176:179], v[192:195], v[26:29]
	v_mfma_f32_16x16x32_bf16 v[14:17], v[168:171], v[200:203], v[14:17]
	v_mfma_f32_16x16x32_bf16 v[10:13], v[176:179], v[200:203], v[10:13]
	v_mfma_f32_16x16x32_bf16 v[6:9], v[168:171], v[244:247], v[6:9]
	v_mfma_f32_16x16x32_bf16 v[2:5], v[176:179], v[244:247], v[2:5]
	s_setprio 0
	s_barrier
	s_add_i32 s21, s21, 2
	s_add_u32 s17, s17, 0x100
	s_addc_u32 s19, s19, 0
	s_cmp_gt_u32 s21, 5
	s_mov_b64 s[44:45], s[46:47]
	s_cbranch_scc0 .LBB0_563
	s_and_b64 vcc, exec, s[14:15]
	s_cbranch_vccz .LBB0_566
	s_barrier

.LBB0_593:
	s_add_u32 s8, s46, 0x100
	s_addc_u32 s9, s47, 0
	s_add_i32 s52, 0, 0x10000
	s_cmp_eq_u32 s40, 12
	s_cselect_b32 vcc_hi, s0, s9
	s_cselect_b32 vcc_lo, s1, s8
	s_cselect_b32 s65, s34, s37
	s_cselect_b32 s64, s35, s36
	s_add_i32 s53, 0, 0x14000
	v_add_u32_e32 v142, s52, v203
	v_add_u32_e32 v158, s53, v203
	ds_read_b128 v[130:133], v142
	ds_read_b128 v[134:137], v142 offset:1024
	ds_read_b128 v[138:141], v142 offset:2048
	ds_read_b128 v[142:145], v142 offset:3072
	ds_read_b128 v[146:149], v158
	ds_read_b128 v[150:153], v158 offset:1024
	ds_read_b128 v[154:157], v158 offset:2048
	ds_read_b128 v[158:161], v158 offset:3072
	v_lshl_add_u64 v[204:205], s[46:47], 0, v[170:171]
	s_add_i32 m0, s19, 0xc000
	ds_read_b128 v[174:177], v222
	ds_read_b128 v[178:181], v222 offset:1024
	ds_read_b128 v[182:185], v222 offset:2048
	ds_read_b128 v[186:189], v222 offset:3072
	ds_read_b128 v[190:193], v222 offset:4096
	ds_read_b128 v[194:197], v222 offset:5120
	ds_read_b128 v[198:201], v222 offset:6144
	ds_read_b128 v[240:243], v222 offset:7168
	global_load_lds_dwordx4 v[204:205], off
	v_lshl_add_u64 v[204:205], s[46:47], 0, v[172:173]
	s_add_i32 m0, s19, 0xe000
	s_nop 0
	global_load_lds_dwordx4 v[204:205], off
	s_waitcnt vmcnt(8)
	s_waitcnt lgkmcnt(0)
	s_barrier
	s_setprio 1
	s_waitcnt lgkmcnt(0)
	v_mfma_f32_16x16x32_bf16 v[126:129], v[130:133], v[174:177], v[126:129]
	v_mfma_f32_16x16x32_bf16 v[122:125], v[138:141], v[174:177], v[122:125]
	v_mfma_f32_16x16x32_bf16 v[110:113], v[130:133], v[182:185], v[110:113]
	v_mfma_f32_16x16x32_bf16 v[106:109], v[138:141], v[182:185], v[106:109]
	v_mfma_f32_16x16x32_bf16 v[94:97], v[130:133], v[190:193], v[94:97]
	v_mfma_f32_16x16x32_bf16 v[90:93], v[138:141], v[190:193], v[90:93]
	v_mfma_f32_16x16x32_bf16 v[78:81], v[130:133], v[198:201], v[78:81]
	v_mfma_f32_16x16x32_bf16 v[74:77], v[138:141], v[198:201], v[74:77]
	v_mfma_f32_16x16x32_bf16 v[126:129], v[134:137], v[178:181], v[126:129]
	v_mfma_f32_16x16x32_bf16 v[122:125], v[142:145], v[178:181], v[122:125]
	v_mfma_f32_16x16x32_bf16 v[110:113], v[134:137], v[186:189], v[110:113]
	v_mfma_f32_16x16x32_bf16 v[106:109], v[142:145], v[186:189], v[106:109]
	v_mfma_f32_16x16x32_bf16 v[94:97], v[134:137], v[194:197], v[94:97]
	v_mfma_f32_16x16x32_bf16 v[90:93], v[142:145], v[194:197], v[90:93]
	v_mfma_f32_16x16x32_bf16 v[78:81], v[134:137], v[240:243], v[78:81]
	v_mfma_f32_16x16x32_bf16 v[74:77], v[142:145], v[240:243], v[74:77]
	v_mfma_f32_16x16x32_bf16 v[118:121], v[146:149], v[174:177], v[118:121]
	v_mfma_f32_16x16x32_bf16 v[114:117], v[154:157], v[174:177], v[114:117]
	v_mfma_f32_16x16x32_bf16 v[102:105], v[146:149], v[182:185], v[102:105]
	v_mfma_f32_16x16x32_bf16 v[98:101], v[154:157], v[182:185], v[98:101]
	v_mfma_f32_16x16x32_bf16 v[86:89], v[146:149], v[190:193], v[86:89]
	v_mfma_f32_16x16x32_bf16 v[82:85], v[154:157], v[190:193], v[82:85]
	v_mfma_f32_16x16x32_bf16 v[70:73], v[146:149], v[198:201], v[70:73]
	v_mfma_f32_16x16x32_bf16 v[66:69], v[154:157], v[198:201], v[66:69]
	v_mfma_f32_16x16x32_bf16 v[118:121], v[150:153], v[178:181], v[118:121]
	v_mfma_f32_16x16x32_bf16 v[114:117], v[158:161], v[178:181], v[114:117]
	v_mfma_f32_16x16x32_bf16 v[102:105], v[150:153], v[186:189], v[102:105]
	v_mfma_f32_16x16x32_bf16 v[98:101], v[158:161], v[186:189], v[98:101]
	v_mfma_f32_16x16x32_bf16 v[86:89], v[150:153], v[194:197], v[86:89]
	v_mfma_f32_16x16x32_bf16 v[82:85], v[158:161], v[194:197], v[82:85]
	v_mfma_f32_16x16x32_bf16 v[70:73], v[150:153], v[240:243], v[70:73]
	v_mfma_f32_16x16x32_bf16 v[66:69], v[158:161], v[240:243], v[66:69]
	s_setprio 0
	s_barrier
	s_add_i32 s46, s52, s18
	v_lshl_add_u64 v[204:205], s[64:65], 0, v[164:165]
	s_mov_b32 m0, s46
	ds_read_b128 v[174:177], v222 offset:16384
	ds_read_b128 v[178:181], v222 offset:17408
	ds_read_b128 v[182:185], v222 offset:18432
	ds_read_b128 v[186:189], v222 offset:19456
	ds_read_b128 v[190:193], v222 offset:20480
	ds_read_b128 v[194:197], v222 offset:21504
	ds_read_b128 v[198:201], v222 offset:22528
	ds_read_b128 v[240:243], v222 offset:23552
	global_load_lds_dwordx4 v[204:205], off
	s_add_i32 m0, s46, 0x2000
	s_add_u32 s46, s64, 0x40000
	v_lshl_add_u64 v[206:207], s[64:65], 0, v[168:169]
	s_addc_u32 s47, s65, 0
	s_add_i32 s52, s53, s18
	global_load_lds_dwordx4 v[206:207], off
	v_lshl_add_u64 v[208:209], s[46:47], 0, v[164:165]
	s_mov_b32 m0, s52
	v_lshl_add_u64 v[210:211], vcc, 0, v[166:167]
	global_load_lds_dwordx4 v[208:209], off
	v_lshl_add_u64 v[208:209], s[46:47], 0, v[168:169]
	s_add_i32 m0, s52, 0x2000
	s_nop 0
	global_load_lds_dwordx4 v[208:209], off
	v_lshl_add_u64 v[208:209], vcc, 0, v[162:163]
	s_mov_b32 m0, s19
	s_nop 0
	global_load_lds_dwordx4 v[208:209], off
	s_mov_b32 m0, s45
	s_nop 0
	global_load_lds_dwordx4 v[210:211], off
	s_waitcnt vmcnt(8)
	s_waitcnt lgkmcnt(0)
	s_barrier
	s_setprio 1
	s_waitcnt lgkmcnt(0)
	v_mfma_f32_16x16x32_bf16 v[62:65], v[130:133], v[174:177], v[62:65]
	v_mfma_f32_16x16x32_bf16 v[58:61], v[138:141], v[174:177], v[58:61]
	v_mfma_f32_16x16x32_bf16 v[46:49], v[130:133], v[182:185], v[46:49]
	v_mfma_f32_16x16x32_bf16 v[42:45], v[138:141], v[182:185], v[42:45]
	v_mfma_f32_16x16x32_bf16 v[30:33], v[130:133], v[190:193], v[30:33]
	v_mfma_f32_16x16x32_bf16 v[26:29], v[138:141], v[190:193], v[26:29]
	v_mfma_f32_16x16x32_bf16 v[14:17], v[130:133], v[198:201], v[14:17]
	v_mfma_f32_16x16x32_bf16 v[10:13], v[138:141], v[198:201], v[10:13]
	v_mfma_f32_16x16x32_bf16 v[62:65], v[134:137], v[178:181], v[62:65]
	v_mfma_f32_16x16x32_bf16 v[58:61], v[142:145], v[178:181], v[58:61]
	v_mfma_f32_16x16x32_bf16 v[46:49], v[134:137], v[186:189], v[46:49]
	v_mfma_f32_16x16x32_bf16 v[42:45], v[142:145], v[186:189], v[42:45]
	v_mfma_f32_16x16x32_bf16 v[30:33], v[134:137], v[194:197], v[30:33]
	v_mfma_f32_16x16x32_bf16 v[26:29], v[142:145], v[194:197], v[26:29]
	v_mfma_f32_16x16x32_bf16 v[14:17], v[134:137], v[240:243], v[14:17]
	v_mfma_f32_16x16x32_bf16 v[10:13], v[142:145], v[240:243], v[10:13]
	v_mfma_f32_16x16x32_bf16 v[54:57], v[146:149], v[174:177], v[54:57]
	v_mfma_f32_16x16x32_bf16 v[50:53], v[154:157], v[174:177], v[50:53]
	v_mfma_f32_16x16x32_bf16 v[38:41], v[146:149], v[182:185], v[38:41]
	v_mfma_f32_16x16x32_bf16 v[34:37], v[154:157], v[182:185], v[34:37]
	v_mfma_f32_16x16x32_bf16 v[22:25], v[146:149], v[190:193], v[22:25]
	v_mfma_f32_16x16x32_bf16 v[18:21], v[154:157], v[190:193], v[18:21]
	v_mfma_f32_16x16x32_bf16 v[6:9], v[146:149], v[198:201], v[6:9]
	v_mfma_f32_16x16x32_bf16 v[2:5], v[154:157], v[198:201], v[2:5]
	v_mfma_f32_16x16x32_bf16 v[54:57], v[150:153], v[178:181], v[54:57]
	v_mfma_f32_16x16x32_bf16 v[50:53], v[158:161], v[178:181], v[50:53]
	v_mfma_f32_16x16x32_bf16 v[38:41], v[150:153], v[186:189], v[38:41]
	v_mfma_f32_16x16x32_bf16 v[34:37], v[158:161], v[186:189], v[34:37]
	v_mfma_f32_16x16x32_bf16 v[22:25], v[150:153], v[194:197], v[22:25]
	v_mfma_f32_16x16x32_bf16 v[18:21], v[158:161], v[194:197], v[18:21]
	v_mfma_f32_16x16x32_bf16 v[6:9], v[150:153], v[240:243], v[6:9]
	v_mfma_f32_16x16x32_bf16 v[2:5], v[158:161], v[240:243], v[2:5]
	s_setprio 0
	s_barrier
	s_add_i32 s52, 0, 0x18000
	s_add_i32 s53, 0, 0x1c000
	v_add_u32_e32 v142, s52, v203
	v_add_u32_e32 v158, s53, v203
	ds_read_b128 v[130:133], v142
	ds_read_b128 v[134:137], v142 offset:1024
	ds_read_b128 v[138:141], v142 offset:2048
	ds_read_b128 v[142:145], v142 offset:3072
	ds_read_b128 v[146:149], v158
	ds_read_b128 v[150:153], v158 offset:1024
	ds_read_b128 v[154:157], v158 offset:2048
	ds_read_b128 v[158:161], v158 offset:3072
	s_add_u32 s46, vcc_lo, 0x40000
	s_addc_u32 s47, vcc_hi, 0
	s_mov_b32 m0, s16
	v_lshl_add_u64 v[214:215], s[46:47], 0, v[162:163]
	ds_read_b128 v[174:177], v222 offset:32768
	ds_read_b128 v[178:181], v222 offset:33792
	ds_read_b128 v[182:185], v222 offset:34816
	ds_read_b128 v[186:189], v222 offset:35840
	ds_read_b128 v[190:193], v222 offset:36864
	ds_read_b128 v[194:197], v222 offset:37888
	ds_read_b128 v[198:201], v222 offset:38912
	ds_read_b128 v[240:243], v222 offset:39936
	global_load_lds_dwordx4 v[214:215], off
	v_lshl_add_u64 v[214:215], s[46:47], 0, v[166:167]
	s_mov_b32 m0, s17
	s_nop 0
	global_load_lds_dwordx4 v[214:215], off
	s_waitcnt vmcnt(8)
	s_waitcnt lgkmcnt(0)
	s_barrier
	s_setprio 1
	s_waitcnt lgkmcnt(0)
	v_mfma_f32_16x16x32_bf16 v[126:129], v[130:133], v[174:177], v[126:129]
	v_mfma_f32_16x16x32_bf16 v[122:125], v[138:141], v[174:177], v[122:125]
	v_mfma_f32_16x16x32_bf16 v[110:113], v[130:133], v[182:185], v[110:113]
	v_mfma_f32_16x16x32_bf16 v[106:109], v[138:141], v[182:185], v[106:109]
	v_mfma_f32_16x16x32_bf16 v[94:97], v[130:133], v[190:193], v[94:97]
	v_mfma_f32_16x16x32_bf16 v[90:93], v[138:141], v[190:193], v[90:93]
	v_mfma_f32_16x16x32_bf16 v[78:81], v[130:133], v[198:201], v[78:81]
	v_mfma_f32_16x16x32_bf16 v[74:77], v[138:141], v[198:201], v[74:77]
	v_mfma_f32_16x16x32_bf16 v[126:129], v[134:137], v[178:181], v[126:129]
	v_mfma_f32_16x16x32_bf16 v[122:125], v[142:145], v[178:181], v[122:125]
	v_mfma_f32_16x16x32_bf16 v[110:113], v[134:137], v[186:189], v[110:113]
	v_mfma_f32_16x16x32_bf16 v[106:109], v[142:145], v[186:189], v[106:109]
	v_mfma_f32_16x16x32_bf16 v[94:97], v[134:137], v[194:197], v[94:97]
	v_mfma_f32_16x16x32_bf16 v[90:93], v[142:145], v[194:197], v[90:93]
	v_mfma_f32_16x16x32_bf16 v[78:81], v[134:137], v[240:243], v[78:81]
	v_mfma_f32_16x16x32_bf16 v[74:77], v[142:145], v[240:243], v[74:77]
	v_mfma_f32_16x16x32_bf16 v[118:121], v[146:149], v[174:177], v[118:121]
	v_mfma_f32_16x16x32_bf16 v[114:117], v[154:157], v[174:177], v[114:117]
	v_mfma_f32_16x16x32_bf16 v[102:105], v[146:149], v[182:185], v[102:105]
	v_mfma_f32_16x16x32_bf16 v[98:101], v[154:157], v[182:185], v[98:101]
	v_mfma_f32_16x16x32_bf16 v[86:89], v[146:149], v[190:193], v[86:89]
	v_mfma_f32_16x16x32_bf16 v[82:85], v[154:157], v[190:193], v[82:85]
	v_mfma_f32_16x16x32_bf16 v[70:73], v[146:149], v[198:201], v[70:73]
	v_mfma_f32_16x16x32_bf16 v[66:69], v[154:157], v[198:201], v[66:69]
	v_mfma_f32_16x16x32_bf16 v[118:121], v[150:153], v[178:181], v[118:121]
	v_mfma_f32_16x16x32_bf16 v[114:117], v[158:161], v[178:181], v[114:117]
	v_mfma_f32_16x16x32_bf16 v[102:105], v[150:153], v[186:189], v[102:105]
	v_mfma_f32_16x16x32_bf16 v[98:101], v[158:161], v[186:189], v[98:101]
	v_mfma_f32_16x16x32_bf16 v[86:89], v[150:153], v[194:197], v[86:89]
	v_mfma_f32_16x16x32_bf16 v[82:85], v[158:161], v[194:197], v[82:85]
	v_mfma_f32_16x16x32_bf16 v[70:73], v[150:153], v[240:243], v[70:73]
	v_mfma_f32_16x16x32_bf16 v[66:69], v[158:161], v[240:243], v[66:69]
	s_setprio 0
	s_barrier
	s_add_i32 s46, s52, s18
	v_lshl_add_u64 v[204:205], v[204:205], 0, s[42:43]
	s_mov_b32 m0, s46
	ds_read_b128 v[174:177], v222 offset:49152
	ds_read_b128 v[178:181], v222 offset:50176
	ds_read_b128 v[182:185], v222 offset:51200
	ds_read_b128 v[186:189], v222 offset:52224
	ds_read_b128 v[190:193], v222 offset:53248
	ds_read_b128 v[194:197], v222 offset:54272
	ds_read_b128 v[198:201], v222 offset:55296
	ds_read_b128 v[240:243], v222 offset:56320
	global_load_lds_dwordx4 v[204:205], off
	s_add_i32 m0, s46, 0x2000
	s_add_u32 s46, s64, 0x40080
	v_lshl_add_u64 v[204:205], v[206:207], 0, s[42:43]
	s_addc_u32 s47, s65, 0
	s_add_i32 s52, s53, s18
	global_load_lds_dwordx4 v[204:205], off
	v_lshl_add_u64 v[204:205], s[46:47], 0, v[164:165]
	s_mov_b32 m0, s52
	s_nop 0
	global_load_lds_dwordx4 v[204:205], off
	v_lshl_add_u64 v[204:205], s[46:47], 0, v[168:169]
	s_add_i32 m0, s52, 0x2000
	s_nop 0
	global_load_lds_dwordx4 v[204:205], off
	v_lshl_add_u64 v[204:205], v[208:209], 0, s[42:43]
	s_mov_b32 m0, s4
	s_nop 0
	global_load_lds_dwordx4 v[204:205], off
	v_lshl_add_u64 v[204:205], v[210:211], 0, s[42:43]
	s_mov_b32 m0, s5
	s_nop 0
	global_load_lds_dwordx4 v[204:205], off
	s_waitcnt vmcnt(8)
	s_waitcnt lgkmcnt(0)
	s_barrier
	s_setprio 1
	s_waitcnt lgkmcnt(0)
	v_mfma_f32_16x16x32_bf16 v[62:65], v[130:133], v[174:177], v[62:65]
	v_mfma_f32_16x16x32_bf16 v[58:61], v[138:141], v[174:177], v[58:61]
	v_mfma_f32_16x16x32_bf16 v[46:49], v[130:133], v[182:185], v[46:49]
	v_mfma_f32_16x16x32_bf16 v[42:45], v[138:141], v[182:185], v[42:45]
	v_mfma_f32_16x16x32_bf16 v[30:33], v[130:133], v[190:193], v[30:33]
	v_mfma_f32_16x16x32_bf16 v[26:29], v[138:141], v[190:193], v[26:29]
	v_mfma_f32_16x16x32_bf16 v[14:17], v[130:133], v[198:201], v[14:17]
	v_mfma_f32_16x16x32_bf16 v[10:13], v[138:141], v[198:201], v[10:13]
	v_mfma_f32_16x16x32_bf16 v[62:65], v[134:137], v[178:181], v[62:65]
	v_mfma_f32_16x16x32_bf16 v[58:61], v[142:145], v[178:181], v[58:61]
	v_mfma_f32_16x16x32_bf16 v[46:49], v[134:137], v[186:189], v[46:49]
	v_mfma_f32_16x16x32_bf16 v[42:45], v[142:145], v[186:189], v[42:45]
	v_mfma_f32_16x16x32_bf16 v[30:33], v[134:137], v[194:197], v[30:33]
	v_mfma_f32_16x16x32_bf16 v[26:29], v[142:145], v[194:197], v[26:29]
	v_mfma_f32_16x16x32_bf16 v[14:17], v[134:137], v[240:243], v[14:17]
	v_mfma_f32_16x16x32_bf16 v[10:13], v[142:145], v[240:243], v[10:13]
	v_mfma_f32_16x16x32_bf16 v[54:57], v[146:149], v[174:177], v[54:57]
	v_mfma_f32_16x16x32_bf16 v[50:53], v[154:157], v[174:177], v[50:53]
	v_mfma_f32_16x16x32_bf16 v[38:41], v[146:149], v[182:185], v[38:41]
	v_mfma_f32_16x16x32_bf16 v[34:37], v[154:157], v[182:185], v[34:37]
	v_mfma_f32_16x16x32_bf16 v[22:25], v[146:149], v[190:193], v[22:25]
	v_mfma_f32_16x16x32_bf16 v[18:21], v[154:157], v[190:193], v[18:21]
	v_mfma_f32_16x16x32_bf16 v[6:9], v[146:149], v[198:201], v[6:9]
	v_mfma_f32_16x16x32_bf16 v[2:5], v[154:157], v[198:201], v[2:5]
	v_mfma_f32_16x16x32_bf16 v[54:57], v[150:153], v[178:181], v[54:57]
	v_mfma_f32_16x16x32_bf16 v[50:53], v[158:161], v[178:181], v[50:53]
	v_mfma_f32_16x16x32_bf16 v[38:41], v[150:153], v[186:189], v[38:41]
	v_mfma_f32_16x16x32_bf16 v[34:37], v[158:161], v[186:189], v[34:37]
	v_mfma_f32_16x16x32_bf16 v[22:25], v[150:153], v[194:197], v[22:25]
	v_mfma_f32_16x16x32_bf16 v[18:21], v[158:161], v[194:197], v[18:21]
	v_mfma_f32_16x16x32_bf16 v[6:9], v[150:153], v[240:243], v[6:9]
	v_mfma_f32_16x16x32_bf16 v[2:5], v[158:161], v[240:243], v[2:5]
	s_setprio 0
	s_barrier
	s_add_i32 s40, s40, 2
	s_add_u32 s36, s36, 0x100
	s_addc_u32 s37, s37, 0
	s_cmp_gt_u32 s40, 13
	s_mov_b64 s[46:47], s[8:9]
	s_cbranch_scc0 .LBB0_593
	v_mov_b32_e32 v130, v1
	s_lshl_b32 s47, s74, 8
	s_add_i32 s46, s47, s27
	v_add_u32_e32 v130, s46, v130
	v_add_u32_e32 v134, 16, v130
	v_ashrrev_i32_e32 v131, 31, v130
	v_ashrrev_i32_e32 v135, 31, v134
	v_lshl_add_u64 v[132:133], v[130:131], 4, s[94:95]
	v_lshl_add_u64 v[134:135], v[134:135], 4, s[94:95]
	global_load_dwordx4 v[158:161], v[132:133], off
	global_load_dwordx4 v[150:153], v[134:135], off
	v_add_u32_e32 v132, 32, v130
	v_add_u32_e32 v134, 48, v130
	v_ashrrev_i32_e32 v133, 31, v132
	v_ashrrev_i32_e32 v135, 31, v134
	v_lshl_add_u64 v[132:133], v[132:133], 4, s[94:95]
	v_lshl_add_u64 v[134:135], v[134:135], 4, s[94:95]
	global_load_dwordx4 v[154:157], v[132:133], off
	global_load_dwordx4 v[142:145], v[134:135], off
	v_add_u32_e32 v132, 0x80, v130
	v_add_u32_e32 v134, 0x90, v130
	v_ashrrev_i32_e32 v133, 31, v132
	v_ashrrev_i32_e32 v135, 31, v134
	v_lshl_add_u64 v[132:133], v[132:133], 4, s[94:95]
	v_lshl_add_u64 v[134:135], v[134:135], 4, s[94:95]
	global_load_dwordx4 v[146:149], v[132:133], off
	s_nop 0
	global_load_dwordx4 v[134:137], v[134:135], off
	v_add_u32_e32 v132, 0xa0, v130
	v_add_u32_e32 v130, 0xb0, v130
	v_ashrrev_i32_e32 v133, 31, v132
	v_ashrrev_i32_e32 v131, 31, v130
	v_lshl_add_u64 v[132:133], v[132:133], 4, s[94:95]
	v_lshl_add_u64 v[130:131], v[130:131], 4, s[94:95]
	global_load_dwordx4 v[138:141], v[132:133], off
	s_nop 0
	global_load_dwordx4 v[130:133], v[130:131], off
	s_and_b64 vcc, exec, s[20:21]
	s_cbranch_vccz .LBB0_596
	s_barrier
